# sc1 write-through also on the attention output dword stores (A-layer O partials, B-layer AO) that precede grid barriers
# baseline (speedup 1.0000x reference)
.LBB0_445:
	s_and_saveexec_b64 s[56:57], s[4:5]
	ds_write_b32 v247, v250
	s_or_b64 exec, exec, s[56:57]
	s_waitcnt lgkmcnt(0)
	s_movk_i32 s83, 0x800
	v_lshl_add_u32 v0, v211, 2, s21
	ds_read2_b32 v[2:3], v0 offset1:1
	s_add_u32 s0, s78, s6
	s_addc_u32 s4, s79, s7
	s_waitcnt lgkmcnt(0)
	v_rcp_f32_e32 v4, v2
	v_rcp_f32_e32 v150, v3
	ds_read2_b32 v[2:3], v0 offset0:2 offset1:3
	v_mul_f32_e32 v130, v130, v4
	v_mul_f32_e32 v114, v114, v4
	v_mul_f32_e32 v98, v98, v4
	s_waitcnt lgkmcnt(0)
	v_rcp_f32_e32 v149, v2
	v_rcp_f32_e32 v148, v3
	ds_read2_b32 v[2:3], v0 offset0:8 offset1:9
	v_mul_f32_e32 v82, v82, v4
	v_mul_f32_e32 v66, v66, v4
	v_mul_f32_e32 v50, v50, v4
	v_mul_f32_e32 v34, v34, v4
	s_waitcnt lgkmcnt(0)
	v_rcp_f32_e32 v147, v2
	v_rcp_f32_e32 v146, v3
	ds_read2_b32 v[2:3], v0 offset0:10 offset1:11
	v_mul_f32_e32 v18, v18, v4
	s_waitcnt lgkmcnt(0)
	v_rcp_f32_e32 v15, v2
	v_rcp_f32_e32 v14, v3
	ds_read2_b32 v[2:3], v0 offset0:16 offset1:17
	s_waitcnt lgkmcnt(0)
	v_rcp_f32_e32 v13, v2
	v_rcp_f32_e32 v12, v3
	ds_read2_b32 v[2:3], v0 offset0:18 offset1:19
	s_waitcnt lgkmcnt(0)
	v_rcp_f32_e32 v11, v2
	v_rcp_f32_e32 v10, v3
	ds_read2_b32 v[2:3], v0 offset0:24 offset1:25
	s_waitcnt lgkmcnt(0)
	v_rcp_f32_e32 v9, v2
	v_rcp_f32_e32 v8, v3
	ds_read2_b32 v[2:3], v0 offset0:26 offset1:27
	s_mul_hi_i32 s3, s83, s1
	s_mul_i32 s2, s83, s1
	s_lshl_b64 s[2:3], s[2:3], 1
	s_waitcnt lgkmcnt(0)
	v_rcp_f32_e32 v7, v2
	v_rcp_f32_e32 v6, v3
	s_add_u32 s56, s0, s2
	s_addc_u32 s57, s4, s3
	s_cmp_gt_u32 s82, 1
	s_cbranch_scc0 .Lep_mode0
	s_add_u32 s58, s80, s6
	s_addc_u32 s59, s81, s7
	s_mul_i32 s2, s83, s1
	s_lshl_b32 s2, s2, 1
	s_add_u32 s58, s58, s2
	s_addc_u32 s59, s59, 0
	v_and_b32_e32 v151, 1, v210
	v_cmp_eq_u32_e64 s[60:61], 0, v151
	v_lshlrev_b32_e32 v2, 2, v210
	global_load_dword v224, v2, s[46:47] offset:0
	global_load_dword v225, v2, s[46:47] offset:128
	global_load_dword v226, v2, s[46:47] offset:256
	global_load_dword v227, v2, s[46:47] offset:384
	global_load_dword v228, v2, s[46:47] offset:512
	global_load_dword v229, v2, s[46:47] offset:640
	global_load_dword v230, v2, s[46:47] offset:768
	global_load_dword v231, v2, s[46:47] offset:896
	v_lshlrev_b32_e32 v3, 12, v237
	v_lshl_add_u32 v3, v210, 4, v3
	global_load_dwordx4 v[152:155], v3, s[56:57] sc1
	v_add_u32_e32 v3, 0x2000, v3
	global_load_dwordx4 v[156:159], v3, s[56:57] sc1
	v_add_u32_e32 v3, 0x2000, v3
	global_load_dwordx4 v[160:163], v3, s[56:57] sc1
	v_add_u32_e32 v3, 0x2000, v3
	global_load_dwordx4 v[164:167], v3, s[56:57] sc1
	v_add_u32_e32 v3, 0x2000, v3
	global_load_dwordx4 v[168:171], v3, s[56:57] sc1
	v_add_u32_e32 v3, 0x2000, v3
	global_load_dwordx4 v[172:175], v3, s[56:57] sc1
	v_add_u32_e32 v3, 0x2000, v3
	global_load_dwordx4 v[176:179], v3, s[56:57] sc1
	v_add_u32_e32 v3, 0x2000, v3
	global_load_dwordx4 v[180:183], v3, s[56:57] sc1
	v_add_u32_e32 v3, 0x2000, v3
	global_load_dwordx4 v[184:187], v3, s[56:57] sc1
	v_add_u32_e32 v3, 0x2000, v3
	global_load_dwordx4 v[188:191], v3, s[56:57] sc1
	v_add_u32_e32 v3, 0x2000, v3
	global_load_dwordx4 v[192:195], v3, s[56:57] sc1
	v_add_u32_e32 v3, 0x2000, v3
	global_load_dwordx4 v[196:199], v3, s[56:57] sc1
	v_add_u32_e32 v3, 0x2000, v3
	global_load_dwordx4 v[200:203], v3, s[56:57] sc1
	v_add_u32_e32 v3, 0x2000, v3
	global_load_dwordx4 v[204:207], v3, s[56:57] sc1
	v_add_u32_e32 v3, 0x2000, v3
	global_load_dwordx4 v[216:219], v3, s[56:57] sc1
	v_add_u32_e32 v3, 0x2000, v3
	global_load_dwordx4 v[220:223], v3, s[56:57] sc1
	v_lshlrev_b32_e32 v212, 2, v210
	v_lshlrev_b32_e32 v213, 7, v237
	v_xad_u32 v0, v212, 64, v213
	v_lshlrev_b32_e32 v212, 14, v237
	v_lshl_add_u32 v212, v210, 1, v212
	v_mul_u32_u24_e32 v213, 62, v151
	v_add_u32_e32 v212, v212, v213
	s_waitcnt vmcnt(16)
	v_mul_f32_e32 v224, v236, v224
	v_mul_f32_e32 v225, v236, v225
	v_mul_f32_e32 v226, v236, v226
	v_mul_f32_e32 v227, v236, v227
	v_mul_f32_e32 v228, v236, v228
	v_mul_f32_e32 v229, v236, v229
	v_mul_f32_e32 v230, v236, v230
	v_mul_f32_e32 v231, v236, v231
	s_waitcnt vmcnt(15)
	v_lshlrev_b32_e32 v250, 16, v152
	v_fma_f32 v240, -v17, v130, v250
	v_and_b32_e32 v250, 0xffff0000, v152
	v_fma_f32 v241, -v17, v114, v250
	v_lshlrev_b32_e32 v250, 16, v153
	v_fma_f32 v242, -v17, v98, v250
	v_and_b32_e32 v250, 0xffff0000, v153
	v_fma_f32 v243, -v17, v82, v250
	v_lshlrev_b32_e32 v250, 16, v154
	v_fma_f32 v245, -v17, v66, v250
	v_and_b32_e32 v250, 0xffff0000, v154
	v_fma_f32 v246, -v17, v50, v250
	v_lshlrev_b32_e32 v250, 16, v155
	v_fma_f32 v247, -v17, v34, v250
	v_and_b32_e32 v250, 0xffff0000, v155
	v_fma_f32 v248, -v17, v18, v250
	v_mul_f32_e32 v251, v241, v241
	v_fmac_f32_e32 v251, v240, v240
	v_fmac_f32_e32 v251, v242, v242
	v_fmac_f32_e32 v251, v243, v243
	v_fmac_f32_e32 v251, v245, v245
	v_fmac_f32_e32 v251, v246, v246
	v_fmac_f32_e32 v251, v247, v247
	v_fmac_f32_e32 v251, v248, v248
	s_nop 1
	v_add_f32_dpp v251, v251, v251 quad_perm:[1,0,3,2] row_mask:0xf bank_mask:0xf bound_ctrl:1
	s_nop 1
	v_add_f32_dpp v251, v251, v251 quad_perm:[2,3,0,1] row_mask:0xf bank_mask:0xf bound_ctrl:1
	s_nop 1
	v_add_f32_dpp v251, v251, v251 row_half_mirror row_mask:0xf bank_mask:0xf bound_ctrl:1
	s_nop 1
	v_add_f32_dpp v251, v251, v251 row_mirror row_mask:0xf bank_mask:0xf bound_ctrl:1
	ds_bpermute_b32 v252, v0, v251
	s_waitcnt lgkmcnt(0)
	v_add_f32_e32 v251, v251, v252
	v_fmamk_f32 v251, v251, 0x3b800000, v238
	v_mul_f32_e32 v252, 0x4f800000, v251
	v_cmp_gt_f32_e32 vcc, s24, v251
	s_nop 1
	v_cndmask_b32_e32 v251, v251, v252, vcc
	v_sqrt_f32_e32 v252, v251
	s_nop 0
	v_add_u32_e32 v249, -1, v252
	v_fma_f32 v250, -v249, v252, v251
	v_cmp_ge_f32_e64 s[6:7], 0, v250
	v_add_u32_e32 v250, 1, v252
	s_nop 0
	v_cndmask_b32_e64 v249, v252, v249, s[6:7]
	v_fma_f32 v252, -v250, v252, v251
	v_cmp_lt_f32_e64 s[6:7], 0, v252
	s_nop 1
	v_cndmask_b32_e64 v252, v249, v250, s[6:7]
	v_mul_f32_e32 v249, 0x37800000, v252
	v_cndmask_b32_e32 v252, v252, v249, vcc
	v_cmp_class_f32_e32 vcc, v251, v239
	s_nop 1
	v_cndmask_b32_e32 v251, v252, v251, vcc
	v_div_scale_f32 v252, s[2:3], v251, v251, 1.0
	v_rcp_f32_e32 v249, v252
	s_nop 0
	v_fma_f32 v250, -v252, v249, 1.0
	v_fmac_f32_e32 v249, v250, v249
	v_div_scale_f32 v250, vcc, 1.0, v251, 1.0
	v_mul_f32_e32 v253, v250, v249
	v_fma_f32 v213, -v252, v253, v250
	v_fmac_f32_e32 v253, v213, v249
	v_fma_f32 v252, -v252, v253, v250
	v_div_fmas_f32 v252, v252, v249, v253
	v_div_fixup_f32 v253, v252, v251, 1.0
	v_mul_f32_e32 v240, v240, v253
	v_mul_f32_e32 v241, v241, v253
	v_mul_f32_e32 v242, v242, v253
	v_mul_f32_e32 v243, v243, v253
	v_mul_f32_e32 v245, v245, v253
	v_mul_f32_e32 v246, v246, v253
	v_mul_f32_e32 v247, v247, v253
	v_mul_f32_e32 v248, v248, v253
	v_mul_f32_e32 v240, v224, v240
	v_mul_f32_e32 v241, v225, v241
	v_mul_f32_e32 v242, v226, v242
	v_mul_f32_e32 v243, v227, v243
	v_mul_f32_e32 v245, v228, v245
	v_mul_f32_e32 v246, v229, v246
	v_mul_f32_e32 v247, v230, v247
	v_mul_f32_e32 v248, v231, v248
	v_add_u32_e32 v249, 0x0, v212
	v_mov_b32_dpp v232, v240 quad_perm:[1,0,3,2] row_mask:0xf bank_mask:0xf bound_ctrl:1
	v_mov_b32_dpp v233, v241 quad_perm:[1,0,3,2] row_mask:0xf bank_mask:0xf bound_ctrl:1
	v_mov_b32_dpp v234, v242 quad_perm:[1,0,3,2] row_mask:0xf bank_mask:0xf bound_ctrl:1
	v_mov_b32_dpp v235, v243 quad_perm:[1,0,3,2] row_mask:0xf bank_mask:0xf bound_ctrl:1
	v_mov_b32_dpp v2, v245 quad_perm:[1,0,3,2] row_mask:0xf bank_mask:0xf bound_ctrl:1
	v_mov_b32_dpp v3, v246 quad_perm:[1,0,3,2] row_mask:0xf bank_mask:0xf bound_ctrl:1
	v_mov_b32_dpp v5, v247 quad_perm:[1,0,3,2] row_mask:0xf bank_mask:0xf bound_ctrl:1
	v_mov_b32_dpp v151, v248 quad_perm:[1,0,3,2] row_mask:0xf bank_mask:0xf bound_ctrl:1
	v_cvt_pk_bf16_f32 v232, v240, v232
	v_cvt_pk_bf16_f32 v233, v233, v241
	v_cndmask_b32_e64 v232, v233, v232, s[60:61]
	global_store_dword v249, v232, s[58:59] offset:0 sc1
	v_cvt_pk_bf16_f32 v234, v242, v234
	v_cvt_pk_bf16_f32 v235, v235, v243
	v_cndmask_b32_e64 v234, v235, v234, s[60:61]
	global_store_dword v249, v234, s[58:59] offset:128 sc1
	v_cvt_pk_bf16_f32 v2, v245, v2
	v_cvt_pk_bf16_f32 v3, v3, v246
	v_cndmask_b32_e64 v2, v3, v2, s[60:61]
	global_store_dword v249, v2, s[58:59] offset:256 sc1
	v_cvt_pk_bf16_f32 v5, v247, v5
	v_cvt_pk_bf16_f32 v151, v151, v248
	v_cndmask_b32_e64 v5, v151, v5, s[60:61]
	global_store_dword v249, v5, s[58:59] offset:384 sc1
	s_waitcnt vmcnt(18)
	v_lshlrev_b32_e32 v250, 16, v156
	v_mul_f32_e32 v249, v131, v150
	v_fma_f32 v240, -v17, v249, v250
	v_and_b32_e32 v250, 0xffff0000, v156
	v_mul_f32_e32 v249, v115, v150
	v_fma_f32 v241, -v17, v249, v250
	v_lshlrev_b32_e32 v250, 16, v157
	v_mul_f32_e32 v249, v99, v150
	v_fma_f32 v242, -v17, v249, v250
	v_and_b32_e32 v250, 0xffff0000, v157
	v_mul_f32_e32 v249, v83, v150
	v_fma_f32 v243, -v17, v249, v250
	v_lshlrev_b32_e32 v250, 16, v158
	v_mul_f32_e32 v249, v67, v150
	v_fma_f32 v245, -v17, v249, v250
	v_and_b32_e32 v250, 0xffff0000, v158
	v_mul_f32_e32 v249, v51, v150
	v_fma_f32 v246, -v17, v249, v250
	v_lshlrev_b32_e32 v250, 16, v159
	v_mul_f32_e32 v249, v35, v150
	v_fma_f32 v247, -v17, v249, v250
	v_and_b32_e32 v250, 0xffff0000, v159
	v_mul_f32_e32 v249, v19, v150
	v_fma_f32 v248, -v17, v249, v250
	v_mul_f32_e32 v251, v241, v241
	v_fmac_f32_e32 v251, v240, v240
	v_fmac_f32_e32 v251, v242, v242
	v_fmac_f32_e32 v251, v243, v243
	v_fmac_f32_e32 v251, v245, v245
	v_fmac_f32_e32 v251, v246, v246
	v_fmac_f32_e32 v251, v247, v247
	v_fmac_f32_e32 v251, v248, v248
	s_nop 1
	v_add_f32_dpp v251, v251, v251 quad_perm:[1,0,3,2] row_mask:0xf bank_mask:0xf bound_ctrl:1
	s_nop 1
	v_add_f32_dpp v251, v251, v251 quad_perm:[2,3,0,1] row_mask:0xf bank_mask:0xf bound_ctrl:1
	s_nop 1
	v_add_f32_dpp v251, v251, v251 row_half_mirror row_mask:0xf bank_mask:0xf bound_ctrl:1
	s_nop 1
	v_add_f32_dpp v251, v251, v251 row_mirror row_mask:0xf bank_mask:0xf bound_ctrl:1
	ds_bpermute_b32 v252, v0, v251
	s_waitcnt lgkmcnt(0)
	v_add_f32_e32 v251, v251, v252
	v_fmamk_f32 v251, v251, 0x3b800000, v238
	v_mul_f32_e32 v252, 0x4f800000, v251
	v_cmp_gt_f32_e32 vcc, s24, v251
	s_nop 1
	v_cndmask_b32_e32 v251, v251, v252, vcc
	v_sqrt_f32_e32 v252, v251
	s_nop 0
	v_add_u32_e32 v249, -1, v252
	v_fma_f32 v250, -v249, v252, v251
	v_cmp_ge_f32_e64 s[6:7], 0, v250
	v_add_u32_e32 v250, 1, v252
	s_nop 0
	v_cndmask_b32_e64 v249, v252, v249, s[6:7]
	v_fma_f32 v252, -v250, v252, v251
	v_cmp_lt_f32_e64 s[6:7], 0, v252
	s_nop 1
	v_cndmask_b32_e64 v252, v249, v250, s[6:7]
	v_mul_f32_e32 v249, 0x37800000, v252
	v_cndmask_b32_e32 v252, v252, v249, vcc
	v_cmp_class_f32_e32 vcc, v251, v239
	s_nop 1
	v_cndmask_b32_e32 v251, v252, v251, vcc
	v_div_scale_f32 v252, s[2:3], v251, v251, 1.0
	v_rcp_f32_e32 v249, v252
	s_nop 0
	v_fma_f32 v250, -v252, v249, 1.0
	v_fmac_f32_e32 v249, v250, v249
	v_div_scale_f32 v250, vcc, 1.0, v251, 1.0
	v_mul_f32_e32 v253, v250, v249
	v_fma_f32 v213, -v252, v253, v250
	v_fmac_f32_e32 v253, v213, v249
	v_fma_f32 v252, -v252, v253, v250
	v_div_fmas_f32 v252, v252, v249, v253
	v_div_fixup_f32 v253, v252, v251, 1.0
	v_mul_f32_e32 v240, v240, v253
	v_mul_f32_e32 v241, v241, v253
	v_mul_f32_e32 v242, v242, v253
	v_mul_f32_e32 v243, v243, v253
	v_mul_f32_e32 v245, v245, v253
	v_mul_f32_e32 v246, v246, v253
	v_mul_f32_e32 v247, v247, v253
	v_mul_f32_e32 v248, v248, v253
	v_mul_f32_e32 v240, v224, v240
	v_mul_f32_e32 v241, v225, v241
	v_mul_f32_e32 v242, v226, v242
	v_mul_f32_e32 v243, v227, v243
	v_mul_f32_e32 v245, v228, v245
	v_mul_f32_e32 v246, v229, v246
	v_mul_f32_e32 v247, v230, v247
	v_mul_f32_e32 v248, v231, v248
	v_add_u32_e32 v249, 0x1000, v212
	v_mov_b32_dpp v232, v240 quad_perm:[1,0,3,2] row_mask:0xf bank_mask:0xf bound_ctrl:1
	v_mov_b32_dpp v233, v241 quad_perm:[1,0,3,2] row_mask:0xf bank_mask:0xf bound_ctrl:1
	v_mov_b32_dpp v234, v242 quad_perm:[1,0,3,2] row_mask:0xf bank_mask:0xf bound_ctrl:1
	v_mov_b32_dpp v235, v243 quad_perm:[1,0,3,2] row_mask:0xf bank_mask:0xf bound_ctrl:1
	v_mov_b32_dpp v2, v245 quad_perm:[1,0,3,2] row_mask:0xf bank_mask:0xf bound_ctrl:1
	v_mov_b32_dpp v3, v246 quad_perm:[1,0,3,2] row_mask:0xf bank_mask:0xf bound_ctrl:1
	v_mov_b32_dpp v5, v247 quad_perm:[1,0,3,2] row_mask:0xf bank_mask:0xf bound_ctrl:1
	v_mov_b32_dpp v151, v248 quad_perm:[1,0,3,2] row_mask:0xf bank_mask:0xf bound_ctrl:1
	v_cvt_pk_bf16_f32 v232, v240, v232
	v_cvt_pk_bf16_f32 v233, v233, v241
	v_cndmask_b32_e64 v232, v233, v232, s[60:61]
	global_store_dword v249, v232, s[58:59] offset:0 sc1
	v_cvt_pk_bf16_f32 v234, v242, v234
	v_cvt_pk_bf16_f32 v235, v235, v243
	v_cndmask_b32_e64 v234, v235, v234, s[60:61]
	global_store_dword v249, v234, s[58:59] offset:128 sc1
	v_cvt_pk_bf16_f32 v2, v245, v2
	v_cvt_pk_bf16_f32 v3, v3, v246
	v_cndmask_b32_e64 v2, v3, v2, s[60:61]
	global_store_dword v249, v2, s[58:59] offset:256 sc1
	v_cvt_pk_bf16_f32 v5, v247, v5
	v_cvt_pk_bf16_f32 v151, v151, v248
	v_cndmask_b32_e64 v5, v151, v5, s[60:61]
	global_store_dword v249, v5, s[58:59] offset:384 sc1
	s_waitcnt vmcnt(21)
	v_lshlrev_b32_e32 v250, 16, v160
	v_mul_f32_e32 v249, v132, v149
	v_fma_f32 v240, -v17, v249, v250
	v_and_b32_e32 v250, 0xffff0000, v160
	v_mul_f32_e32 v249, v116, v149
	v_fma_f32 v241, -v17, v249, v250
	v_lshlrev_b32_e32 v250, 16, v161
	v_mul_f32_e32 v249, v100, v149
	v_fma_f32 v242, -v17, v249, v250
	v_and_b32_e32 v250, 0xffff0000, v161
	v_mul_f32_e32 v249, v84, v149
	v_fma_f32 v243, -v17, v249, v250
	v_lshlrev_b32_e32 v250, 16, v162
	v_mul_f32_e32 v249, v68, v149
	v_fma_f32 v245, -v17, v249, v250
	v_and_b32_e32 v250, 0xffff0000, v162
	v_mul_f32_e32 v249, v52, v149
	v_fma_f32 v246, -v17, v249, v250
	v_lshlrev_b32_e32 v250, 16, v163
	v_mul_f32_e32 v249, v36, v149
	v_fma_f32 v247, -v17, v249, v250
	v_and_b32_e32 v250, 0xffff0000, v163
	v_mul_f32_e32 v249, v20, v149
	v_fma_f32 v248, -v17, v249, v250
	v_mul_f32_e32 v251, v241, v241
	v_fmac_f32_e32 v251, v240, v240
	v_fmac_f32_e32 v251, v242, v242
	v_fmac_f32_e32 v251, v243, v243
	v_fmac_f32_e32 v251, v245, v245
	v_fmac_f32_e32 v251, v246, v246
	v_fmac_f32_e32 v251, v247, v247
	v_fmac_f32_e32 v251, v248, v248
	s_nop 1
	v_add_f32_dpp v251, v251, v251 quad_perm:[1,0,3,2] row_mask:0xf bank_mask:0xf bound_ctrl:1
	s_nop 1
	v_add_f32_dpp v251, v251, v251 quad_perm:[2,3,0,1] row_mask:0xf bank_mask:0xf bound_ctrl:1
	s_nop 1
	v_add_f32_dpp v251, v251, v251 row_half_mirror row_mask:0xf bank_mask:0xf bound_ctrl:1
	s_nop 1
	v_add_f32_dpp v251, v251, v251 row_mirror row_mask:0xf bank_mask:0xf bound_ctrl:1
	ds_bpermute_b32 v252, v0, v251
	s_waitcnt lgkmcnt(0)
	v_add_f32_e32 v251, v251, v252
	v_fmamk_f32 v251, v251, 0x3b800000, v238
	v_mul_f32_e32 v252, 0x4f800000, v251
	v_cmp_gt_f32_e32 vcc, s24, v251
	s_nop 1
	v_cndmask_b32_e32 v251, v251, v252, vcc
	v_sqrt_f32_e32 v252, v251
	s_nop 0
	v_add_u32_e32 v249, -1, v252
	v_fma_f32 v250, -v249, v252, v251
	v_cmp_ge_f32_e64 s[6:7], 0, v250
	v_add_u32_e32 v250, 1, v252
	s_nop 0
	v_cndmask_b32_e64 v249, v252, v249, s[6:7]
	v_fma_f32 v252, -v250, v252, v251
	v_cmp_lt_f32_e64 s[6:7], 0, v252
	s_nop 1
	v_cndmask_b32_e64 v252, v249, v250, s[6:7]
	v_mul_f32_e32 v249, 0x37800000, v252
	v_cndmask_b32_e32 v252, v252, v249, vcc
	v_cmp_class_f32_e32 vcc, v251, v239
	s_nop 1
	v_cndmask_b32_e32 v251, v252, v251, vcc
	v_div_scale_f32 v252, s[2:3], v251, v251, 1.0
	v_rcp_f32_e32 v249, v252
	s_nop 0
	v_fma_f32 v250, -v252, v249, 1.0
	v_fmac_f32_e32 v249, v250, v249
	v_div_scale_f32 v250, vcc, 1.0, v251, 1.0
	v_mul_f32_e32 v253, v250, v249
	v_fma_f32 v213, -v252, v253, v250
	v_fmac_f32_e32 v253, v213, v249
	v_fma_f32 v252, -v252, v253, v250
	v_div_fmas_f32 v252, v252, v249, v253
	v_div_fixup_f32 v253, v252, v251, 1.0
	v_mul_f32_e32 v240, v240, v253
	v_mul_f32_e32 v241, v241, v253
	v_mul_f32_e32 v242, v242, v253
	v_mul_f32_e32 v243, v243, v253
	v_mul_f32_e32 v245, v245, v253
	v_mul_f32_e32 v246, v246, v253
	v_mul_f32_e32 v247, v247, v253
	v_mul_f32_e32 v248, v248, v253
	v_mul_f32_e32 v240, v224, v240
	v_mul_f32_e32 v241, v225, v241
	v_mul_f32_e32 v242, v226, v242
	v_mul_f32_e32 v243, v227, v243
	v_mul_f32_e32 v245, v228, v245
	v_mul_f32_e32 v246, v229, v246
	v_mul_f32_e32 v247, v230, v247
	v_mul_f32_e32 v248, v231, v248
	v_add_u32_e32 v249, 0x2000, v212
	v_mov_b32_dpp v232, v240 quad_perm:[1,0,3,2] row_mask:0xf bank_mask:0xf bound_ctrl:1
	v_mov_b32_dpp v233, v241 quad_perm:[1,0,3,2] row_mask:0xf bank_mask:0xf bound_ctrl:1
	v_mov_b32_dpp v234, v242 quad_perm:[1,0,3,2] row_mask:0xf bank_mask:0xf bound_ctrl:1
	v_mov_b32_dpp v235, v243 quad_perm:[1,0,3,2] row_mask:0xf bank_mask:0xf bound_ctrl:1
	v_mov_b32_dpp v2, v245 quad_perm:[1,0,3,2] row_mask:0xf bank_mask:0xf bound_ctrl:1
	v_mov_b32_dpp v3, v246 quad_perm:[1,0,3,2] row_mask:0xf bank_mask:0xf bound_ctrl:1
	v_mov_b32_dpp v5, v247 quad_perm:[1,0,3,2] row_mask:0xf bank_mask:0xf bound_ctrl:1
	v_mov_b32_dpp v151, v248 quad_perm:[1,0,3,2] row_mask:0xf bank_mask:0xf bound_ctrl:1
	v_cvt_pk_bf16_f32 v232, v240, v232
	v_cvt_pk_bf16_f32 v233, v233, v241
	v_cndmask_b32_e64 v232, v233, v232, s[60:61]
	global_store_dword v249, v232, s[58:59] offset:0 sc1
	v_cvt_pk_bf16_f32 v234, v242, v234
	v_cvt_pk_bf16_f32 v235, v235, v243
	v_cndmask_b32_e64 v234, v235, v234, s[60:61]
	global_store_dword v249, v234, s[58:59] offset:128 sc1
	v_cvt_pk_bf16_f32 v2, v245, v2
	v_cvt_pk_bf16_f32 v3, v3, v246
	v_cndmask_b32_e64 v2, v3, v2, s[60:61]
	global_store_dword v249, v2, s[58:59] offset:256 sc1
	v_cvt_pk_bf16_f32 v5, v247, v5
	v_cvt_pk_bf16_f32 v151, v151, v248
	v_cndmask_b32_e64 v5, v151, v5, s[60:61]
	global_store_dword v249, v5, s[58:59] offset:384 sc1
	s_waitcnt vmcnt(24)
	v_lshlrev_b32_e32 v250, 16, v164
	v_mul_f32_e32 v249, v133, v148
	v_fma_f32 v240, -v17, v249, v250
	v_and_b32_e32 v250, 0xffff0000, v164
	v_mul_f32_e32 v249, v117, v148
	v_fma_f32 v241, -v17, v249, v250
	v_lshlrev_b32_e32 v250, 16, v165
	v_mul_f32_e32 v249, v101, v148
	v_fma_f32 v242, -v17, v249, v250
	v_and_b32_e32 v250, 0xffff0000, v165
	v_mul_f32_e32 v249, v85, v148
	v_fma_f32 v243, -v17, v249, v250
	v_lshlrev_b32_e32 v250, 16, v166
	v_mul_f32_e32 v249, v69, v148
	v_fma_f32 v245, -v17, v249, v250
	v_and_b32_e32 v250, 0xffff0000, v166
	v_mul_f32_e32 v249, v53, v148
	v_fma_f32 v246, -v17, v249, v250
	v_lshlrev_b32_e32 v250, 16, v167
	v_mul_f32_e32 v249, v37, v148
	v_fma_f32 v247, -v17, v249, v250
	v_and_b32_e32 v250, 0xffff0000, v167
	v_mul_f32_e32 v249, v21, v148
	v_fma_f32 v248, -v17, v249, v250
	v_mul_f32_e32 v251, v241, v241
	v_fmac_f32_e32 v251, v240, v240
	v_fmac_f32_e32 v251, v242, v242
	v_fmac_f32_e32 v251, v243, v243
	v_fmac_f32_e32 v251, v245, v245
	v_fmac_f32_e32 v251, v246, v246
	v_fmac_f32_e32 v251, v247, v247
	v_fmac_f32_e32 v251, v248, v248
	s_nop 1
	v_add_f32_dpp v251, v251, v251 quad_perm:[1,0,3,2] row_mask:0xf bank_mask:0xf bound_ctrl:1
	s_nop 1
	v_add_f32_dpp v251, v251, v251 quad_perm:[2,3,0,1] row_mask:0xf bank_mask:0xf bound_ctrl:1
	s_nop 1
	v_add_f32_dpp v251, v251, v251 row_half_mirror row_mask:0xf bank_mask:0xf bound_ctrl:1
	s_nop 1
	v_add_f32_dpp v251, v251, v251 row_mirror row_mask:0xf bank_mask:0xf bound_ctrl:1
	ds_bpermute_b32 v252, v0, v251
	s_waitcnt lgkmcnt(0)
	v_add_f32_e32 v251, v251, v252
	v_fmamk_f32 v251, v251, 0x3b800000, v238
	v_mul_f32_e32 v252, 0x4f800000, v251
	v_cmp_gt_f32_e32 vcc, s24, v251
	s_nop 1
	v_cndmask_b32_e32 v251, v251, v252, vcc
	v_sqrt_f32_e32 v252, v251
	s_nop 0
	v_add_u32_e32 v249, -1, v252
	v_fma_f32 v250, -v249, v252, v251
	v_cmp_ge_f32_e64 s[6:7], 0, v250
	v_add_u32_e32 v250, 1, v252
	s_nop 0
	v_cndmask_b32_e64 v249, v252, v249, s[6:7]
	v_fma_f32 v252, -v250, v252, v251
	v_cmp_lt_f32_e64 s[6:7], 0, v252
	s_nop 1
	v_cndmask_b32_e64 v252, v249, v250, s[6:7]
	v_mul_f32_e32 v249, 0x37800000, v252
	v_cndmask_b32_e32 v252, v252, v249, vcc
	v_cmp_class_f32_e32 vcc, v251, v239
	s_nop 1
	v_cndmask_b32_e32 v251, v252, v251, vcc
	v_div_scale_f32 v252, s[2:3], v251, v251, 1.0
	v_rcp_f32_e32 v249, v252
	s_nop 0
	v_fma_f32 v250, -v252, v249, 1.0
	v_fmac_f32_e32 v249, v250, v249
	v_div_scale_f32 v250, vcc, 1.0, v251, 1.0
	v_mul_f32_e32 v253, v250, v249
	v_fma_f32 v213, -v252, v253, v250
	v_fmac_f32_e32 v253, v213, v249
	v_fma_f32 v252, -v252, v253, v250
	v_div_fmas_f32 v252, v252, v249, v253
	v_div_fixup_f32 v253, v252, v251, 1.0
	v_mul_f32_e32 v240, v240, v253
	v_mul_f32_e32 v241, v241, v253
	v_mul_f32_e32 v242, v242, v253
	v_mul_f32_e32 v243, v243, v253
	v_mul_f32_e32 v245, v245, v253
	v_mul_f32_e32 v246, v246, v253
	v_mul_f32_e32 v247, v247, v253
	v_mul_f32_e32 v248, v248, v253
	v_mul_f32_e32 v240, v224, v240
	v_mul_f32_e32 v241, v225, v241
	v_mul_f32_e32 v242, v226, v242
	v_mul_f32_e32 v243, v227, v243
	v_mul_f32_e32 v245, v228, v245
	v_mul_f32_e32 v246, v229, v246
	v_mul_f32_e32 v247, v230, v247
	v_mul_f32_e32 v248, v231, v248
	v_add_u32_e32 v249, 0x3000, v212
	v_mov_b32_dpp v232, v240 quad_perm:[1,0,3,2] row_mask:0xf bank_mask:0xf bound_ctrl:1
	v_mov_b32_dpp v233, v241 quad_perm:[1,0,3,2] row_mask:0xf bank_mask:0xf bound_ctrl:1
	v_mov_b32_dpp v234, v242 quad_perm:[1,0,3,2] row_mask:0xf bank_mask:0xf bound_ctrl:1
	v_mov_b32_dpp v235, v243 quad_perm:[1,0,3,2] row_mask:0xf bank_mask:0xf bound_ctrl:1
	v_mov_b32_dpp v2, v245 quad_perm:[1,0,3,2] row_mask:0xf bank_mask:0xf bound_ctrl:1
	v_mov_b32_dpp v3, v246 quad_perm:[1,0,3,2] row_mask:0xf bank_mask:0xf bound_ctrl:1
	v_mov_b32_dpp v5, v247 quad_perm:[1,0,3,2] row_mask:0xf bank_mask:0xf bound_ctrl:1
	v_mov_b32_dpp v151, v248 quad_perm:[1,0,3,2] row_mask:0xf bank_mask:0xf bound_ctrl:1
	v_cvt_pk_bf16_f32 v232, v240, v232
	v_cvt_pk_bf16_f32 v233, v233, v241
	v_cndmask_b32_e64 v232, v233, v232, s[60:61]
	global_store_dword v249, v232, s[58:59] offset:0 sc1
	v_cvt_pk_bf16_f32 v234, v242, v234
	v_cvt_pk_bf16_f32 v235, v235, v243
	v_cndmask_b32_e64 v234, v235, v234, s[60:61]
	global_store_dword v249, v234, s[58:59] offset:128 sc1
	v_cvt_pk_bf16_f32 v2, v245, v2
	v_cvt_pk_bf16_f32 v3, v3, v246
	v_cndmask_b32_e64 v2, v3, v2, s[60:61]
	global_store_dword v249, v2, s[58:59] offset:256 sc1
	v_cvt_pk_bf16_f32 v5, v247, v5
	v_cvt_pk_bf16_f32 v151, v151, v248
	v_cndmask_b32_e64 v5, v151, v5, s[60:61]
	global_store_dword v249, v5, s[58:59] offset:384 sc1
	s_waitcnt vmcnt(27)
	v_lshlrev_b32_e32 v250, 16, v168
	v_mul_f32_e32 v249, v134, v147
	v_fma_f32 v240, -v17, v249, v250
	v_and_b32_e32 v250, 0xffff0000, v168
	v_mul_f32_e32 v249, v118, v147
	v_fma_f32 v241, -v17, v249, v250
	v_lshlrev_b32_e32 v250, 16, v169
	v_mul_f32_e32 v249, v102, v147
	v_fma_f32 v242, -v17, v249, v250
	v_and_b32_e32 v250, 0xffff0000, v169
	v_mul_f32_e32 v249, v86, v147
	v_fma_f32 v243, -v17, v249, v250
	v_lshlrev_b32_e32 v250, 16, v170
	v_mul_f32_e32 v249, v70, v147
	v_fma_f32 v245, -v17, v249, v250
	v_and_b32_e32 v250, 0xffff0000, v170
	v_mul_f32_e32 v249, v54, v147
	v_fma_f32 v246, -v17, v249, v250
	v_lshlrev_b32_e32 v250, 16, v171
	v_mul_f32_e32 v249, v38, v147
	v_fma_f32 v247, -v17, v249, v250
	v_and_b32_e32 v250, 0xffff0000, v171
	v_mul_f32_e32 v249, v22, v147
	v_fma_f32 v248, -v17, v249, v250
	v_mul_f32_e32 v251, v241, v241
	v_fmac_f32_e32 v251, v240, v240
	v_fmac_f32_e32 v251, v242, v242
	v_fmac_f32_e32 v251, v243, v243
	v_fmac_f32_e32 v251, v245, v245
	v_fmac_f32_e32 v251, v246, v246
	v_fmac_f32_e32 v251, v247, v247
	v_fmac_f32_e32 v251, v248, v248
	s_nop 1
	v_add_f32_dpp v251, v251, v251 quad_perm:[1,0,3,2] row_mask:0xf bank_mask:0xf bound_ctrl:1
	s_nop 1
	v_add_f32_dpp v251, v251, v251 quad_perm:[2,3,0,1] row_mask:0xf bank_mask:0xf bound_ctrl:1
	s_nop 1
	v_add_f32_dpp v251, v251, v251 row_half_mirror row_mask:0xf bank_mask:0xf bound_ctrl:1
	s_nop 1
	v_add_f32_dpp v251, v251, v251 row_mirror row_mask:0xf bank_mask:0xf bound_ctrl:1
	ds_bpermute_b32 v252, v0, v251
	s_waitcnt lgkmcnt(0)
	v_add_f32_e32 v251, v251, v252
	v_fmamk_f32 v251, v251, 0x3b800000, v238
	v_mul_f32_e32 v252, 0x4f800000, v251
	v_cmp_gt_f32_e32 vcc, s24, v251
	s_nop 1
	v_cndmask_b32_e32 v251, v251, v252, vcc
	v_sqrt_f32_e32 v252, v251
	s_nop 0
	v_add_u32_e32 v249, -1, v252
	v_fma_f32 v250, -v249, v252, v251
	v_cmp_ge_f32_e64 s[6:7], 0, v250
	v_add_u32_e32 v250, 1, v252
	s_nop 0
	v_cndmask_b32_e64 v249, v252, v249, s[6:7]
	v_fma_f32 v252, -v250, v252, v251
	v_cmp_lt_f32_e64 s[6:7], 0, v252
	s_nop 1
	v_cndmask_b32_e64 v252, v249, v250, s[6:7]
	v_mul_f32_e32 v249, 0x37800000, v252
	v_cndmask_b32_e32 v252, v252, v249, vcc
	v_cmp_class_f32_e32 vcc, v251, v239
	s_nop 1
	v_cndmask_b32_e32 v251, v252, v251, vcc
	v_div_scale_f32 v252, s[2:3], v251, v251, 1.0
	v_rcp_f32_e32 v249, v252
	s_nop 0
	v_fma_f32 v250, -v252, v249, 1.0
	v_fmac_f32_e32 v249, v250, v249
	v_div_scale_f32 v250, vcc, 1.0, v251, 1.0
	v_mul_f32_e32 v253, v250, v249
	v_fma_f32 v213, -v252, v253, v250
	v_fmac_f32_e32 v253, v213, v249
	v_fma_f32 v252, -v252, v253, v250
	v_div_fmas_f32 v252, v252, v249, v253
	v_div_fixup_f32 v253, v252, v251, 1.0
	v_mul_f32_e32 v240, v240, v253
	v_mul_f32_e32 v241, v241, v253
	v_mul_f32_e32 v242, v242, v253
	v_mul_f32_e32 v243, v243, v253
	v_mul_f32_e32 v245, v245, v253
	v_mul_f32_e32 v246, v246, v253
	v_mul_f32_e32 v247, v247, v253
	v_mul_f32_e32 v248, v248, v253
	v_mul_f32_e32 v240, v224, v240
	v_mul_f32_e32 v241, v225, v241
	v_mul_f32_e32 v242, v226, v242
	v_mul_f32_e32 v243, v227, v243
	v_mul_f32_e32 v245, v228, v245
	v_mul_f32_e32 v246, v229, v246
	v_mul_f32_e32 v247, v230, v247
	v_mul_f32_e32 v248, v231, v248
	v_add_u32_e32 v249, 0x8000, v212
	v_mov_b32_dpp v232, v240 quad_perm:[1,0,3,2] row_mask:0xf bank_mask:0xf bound_ctrl:1
	v_mov_b32_dpp v233, v241 quad_perm:[1,0,3,2] row_mask:0xf bank_mask:0xf bound_ctrl:1
	v_mov_b32_dpp v234, v242 quad_perm:[1,0,3,2] row_mask:0xf bank_mask:0xf bound_ctrl:1
	v_mov_b32_dpp v235, v243 quad_perm:[1,0,3,2] row_mask:0xf bank_mask:0xf bound_ctrl:1
	v_mov_b32_dpp v2, v245 quad_perm:[1,0,3,2] row_mask:0xf bank_mask:0xf bound_ctrl:1
	v_mov_b32_dpp v3, v246 quad_perm:[1,0,3,2] row_mask:0xf bank_mask:0xf bound_ctrl:1
	v_mov_b32_dpp v5, v247 quad_perm:[1,0,3,2] row_mask:0xf bank_mask:0xf bound_ctrl:1
	v_mov_b32_dpp v151, v248 quad_perm:[1,0,3,2] row_mask:0xf bank_mask:0xf bound_ctrl:1
	v_cvt_pk_bf16_f32 v232, v240, v232
	v_cvt_pk_bf16_f32 v233, v233, v241
	v_cndmask_b32_e64 v232, v233, v232, s[60:61]
	global_store_dword v249, v232, s[58:59] offset:0 sc1
	v_cvt_pk_bf16_f32 v234, v242, v234
	v_cvt_pk_bf16_f32 v235, v235, v243
	v_cndmask_b32_e64 v234, v235, v234, s[60:61]
	global_store_dword v249, v234, s[58:59] offset:128 sc1
	v_cvt_pk_bf16_f32 v2, v245, v2
	v_cvt_pk_bf16_f32 v3, v3, v246
	v_cndmask_b32_e64 v2, v3, v2, s[60:61]
	global_store_dword v249, v2, s[58:59] offset:256 sc1
	v_cvt_pk_bf16_f32 v5, v247, v5
	v_cvt_pk_bf16_f32 v151, v151, v248
	v_cndmask_b32_e64 v5, v151, v5, s[60:61]
	global_store_dword v249, v5, s[58:59] offset:384 sc1
	s_waitcnt vmcnt(30)
	v_lshlrev_b32_e32 v250, 16, v172
	v_mul_f32_e32 v249, v135, v146
	v_fma_f32 v240, -v17, v249, v250
	v_and_b32_e32 v250, 0xffff0000, v172
	v_mul_f32_e32 v249, v119, v146
	v_fma_f32 v241, -v17, v249, v250
	v_lshlrev_b32_e32 v250, 16, v173
	v_mul_f32_e32 v249, v103, v146
	v_fma_f32 v242, -v17, v249, v250
	v_and_b32_e32 v250, 0xffff0000, v173
	v_mul_f32_e32 v249, v87, v146
	v_fma_f32 v243, -v17, v249, v250
	v_lshlrev_b32_e32 v250, 16, v174
	v_mul_f32_e32 v249, v71, v146
	v_fma_f32 v245, -v17, v249, v250
	v_and_b32_e32 v250, 0xffff0000, v174
	v_mul_f32_e32 v249, v55, v146
	v_fma_f32 v246, -v17, v249, v250
	v_lshlrev_b32_e32 v250, 16, v175
	v_mul_f32_e32 v249, v39, v146
	v_fma_f32 v247, -v17, v249, v250
	v_and_b32_e32 v250, 0xffff0000, v175
	v_mul_f32_e32 v249, v23, v146
	v_fma_f32 v248, -v17, v249, v250
	v_mul_f32_e32 v251, v241, v241
	v_fmac_f32_e32 v251, v240, v240
	v_fmac_f32_e32 v251, v242, v242
	v_fmac_f32_e32 v251, v243, v243
	v_fmac_f32_e32 v251, v245, v245
	v_fmac_f32_e32 v251, v246, v246
	v_fmac_f32_e32 v251, v247, v247
	v_fmac_f32_e32 v251, v248, v248
	s_nop 1
	v_add_f32_dpp v251, v251, v251 quad_perm:[1,0,3,2] row_mask:0xf bank_mask:0xf bound_ctrl:1
	s_nop 1
	v_add_f32_dpp v251, v251, v251 quad_perm:[2,3,0,1] row_mask:0xf bank_mask:0xf bound_ctrl:1
	s_nop 1
	v_add_f32_dpp v251, v251, v251 row_half_mirror row_mask:0xf bank_mask:0xf bound_ctrl:1
	s_nop 1
	v_add_f32_dpp v251, v251, v251 row_mirror row_mask:0xf bank_mask:0xf bound_ctrl:1
	ds_bpermute_b32 v252, v0, v251
	s_waitcnt lgkmcnt(0)
	v_add_f32_e32 v251, v251, v252
	v_fmamk_f32 v251, v251, 0x3b800000, v238
	v_mul_f32_e32 v252, 0x4f800000, v251
	v_cmp_gt_f32_e32 vcc, s24, v251
	s_nop 1
	v_cndmask_b32_e32 v251, v251, v252, vcc
	v_sqrt_f32_e32 v252, v251
	s_nop 0
	v_add_u32_e32 v249, -1, v252
	v_fma_f32 v250, -v249, v252, v251
	v_cmp_ge_f32_e64 s[6:7], 0, v250
	v_add_u32_e32 v250, 1, v252
	s_nop 0
	v_cndmask_b32_e64 v249, v252, v249, s[6:7]
	v_fma_f32 v252, -v250, v252, v251
	v_cmp_lt_f32_e64 s[6:7], 0, v252
	s_nop 1
	v_cndmask_b32_e64 v252, v249, v250, s[6:7]
	v_mul_f32_e32 v249, 0x37800000, v252
	v_cndmask_b32_e32 v252, v252, v249, vcc
	v_cmp_class_f32_e32 vcc, v251, v239
	s_nop 1
	v_cndmask_b32_e32 v251, v252, v251, vcc
	v_div_scale_f32 v252, s[2:3], v251, v251, 1.0
	v_rcp_f32_e32 v249, v252
	s_nop 0
	v_fma_f32 v250, -v252, v249, 1.0
	v_fmac_f32_e32 v249, v250, v249
	v_div_scale_f32 v250, vcc, 1.0, v251, 1.0
	v_mul_f32_e32 v253, v250, v249
	v_fma_f32 v213, -v252, v253, v250
	v_fmac_f32_e32 v253, v213, v249
	v_fma_f32 v252, -v252, v253, v250
	v_div_fmas_f32 v252, v252, v249, v253
	v_div_fixup_f32 v253, v252, v251, 1.0
	v_mul_f32_e32 v240, v240, v253
	v_mul_f32_e32 v241, v241, v253
	v_mul_f32_e32 v242, v242, v253
	v_mul_f32_e32 v243, v243, v253
	v_mul_f32_e32 v245, v245, v253
	v_mul_f32_e32 v246, v246, v253
	v_mul_f32_e32 v247, v247, v253
	v_mul_f32_e32 v248, v248, v253
	v_mul_f32_e32 v240, v224, v240
	v_mul_f32_e32 v241, v225, v241
	v_mul_f32_e32 v242, v226, v242
	v_mul_f32_e32 v243, v227, v243
	v_mul_f32_e32 v245, v228, v245
	v_mul_f32_e32 v246, v229, v246
	v_mul_f32_e32 v247, v230, v247
	v_mul_f32_e32 v248, v231, v248
	v_add_u32_e32 v249, 0x9000, v212
	v_mov_b32_dpp v232, v240 quad_perm:[1,0,3,2] row_mask:0xf bank_mask:0xf bound_ctrl:1
	v_mov_b32_dpp v233, v241 quad_perm:[1,0,3,2] row_mask:0xf bank_mask:0xf bound_ctrl:1
	v_mov_b32_dpp v234, v242 quad_perm:[1,0,3,2] row_mask:0xf bank_mask:0xf bound_ctrl:1
	v_mov_b32_dpp v235, v243 quad_perm:[1,0,3,2] row_mask:0xf bank_mask:0xf bound_ctrl:1
	v_mov_b32_dpp v2, v245 quad_perm:[1,0,3,2] row_mask:0xf bank_mask:0xf bound_ctrl:1
	v_mov_b32_dpp v3, v246 quad_perm:[1,0,3,2] row_mask:0xf bank_mask:0xf bound_ctrl:1
	v_mov_b32_dpp v5, v247 quad_perm:[1,0,3,2] row_mask:0xf bank_mask:0xf bound_ctrl:1
	v_mov_b32_dpp v151, v248 quad_perm:[1,0,3,2] row_mask:0xf bank_mask:0xf bound_ctrl:1
	v_cvt_pk_bf16_f32 v232, v240, v232
	v_cvt_pk_bf16_f32 v233, v233, v241
	v_cndmask_b32_e64 v232, v233, v232, s[60:61]
	global_store_dword v249, v232, s[58:59] offset:0 sc1
	v_cvt_pk_bf16_f32 v234, v242, v234
	v_cvt_pk_bf16_f32 v235, v235, v243
	v_cndmask_b32_e64 v234, v235, v234, s[60:61]
	global_store_dword v249, v234, s[58:59] offset:128 sc1
	v_cvt_pk_bf16_f32 v2, v245, v2
	v_cvt_pk_bf16_f32 v3, v3, v246
	v_cndmask_b32_e64 v2, v3, v2, s[60:61]
	global_store_dword v249, v2, s[58:59] offset:256 sc1
	v_cvt_pk_bf16_f32 v5, v247, v5
	v_cvt_pk_bf16_f32 v151, v151, v248
	v_cndmask_b32_e64 v5, v151, v5, s[60:61]
	global_store_dword v249, v5, s[58:59] offset:384 sc1
	s_waitcnt vmcnt(33)
	v_lshlrev_b32_e32 v250, 16, v176
	v_mul_f32_e32 v249, v136, v15
	v_fma_f32 v240, -v17, v249, v250
	v_and_b32_e32 v250, 0xffff0000, v176
	v_mul_f32_e32 v249, v120, v15
	v_fma_f32 v241, -v17, v249, v250
	v_lshlrev_b32_e32 v250, 16, v177
	v_mul_f32_e32 v249, v104, v15
	v_fma_f32 v242, -v17, v249, v250
	v_and_b32_e32 v250, 0xffff0000, v177
	v_mul_f32_e32 v249, v88, v15
	v_fma_f32 v243, -v17, v249, v250
	v_lshlrev_b32_e32 v250, 16, v178
	v_mul_f32_e32 v249, v72, v15
	v_fma_f32 v245, -v17, v249, v250
	v_and_b32_e32 v250, 0xffff0000, v178
	v_mul_f32_e32 v249, v56, v15
	v_fma_f32 v246, -v17, v249, v250
	v_lshlrev_b32_e32 v250, 16, v179
	v_mul_f32_e32 v249, v40, v15
	v_fma_f32 v247, -v17, v249, v250
	v_and_b32_e32 v250, 0xffff0000, v179
	v_mul_f32_e32 v249, v24, v15
	v_fma_f32 v248, -v17, v249, v250
	v_mul_f32_e32 v251, v241, v241
	v_fmac_f32_e32 v251, v240, v240
	v_fmac_f32_e32 v251, v242, v242
	v_fmac_f32_e32 v251, v243, v243
	v_fmac_f32_e32 v251, v245, v245
	v_fmac_f32_e32 v251, v246, v246
	v_fmac_f32_e32 v251, v247, v247
	v_fmac_f32_e32 v251, v248, v248
	s_nop 1
	v_add_f32_dpp v251, v251, v251 quad_perm:[1,0,3,2] row_mask:0xf bank_mask:0xf bound_ctrl:1
	s_nop 1
	v_add_f32_dpp v251, v251, v251 quad_perm:[2,3,0,1] row_mask:0xf bank_mask:0xf bound_ctrl:1
	s_nop 1
	v_add_f32_dpp v251, v251, v251 row_half_mirror row_mask:0xf bank_mask:0xf bound_ctrl:1
	s_nop 1
	v_add_f32_dpp v251, v251, v251 row_mirror row_mask:0xf bank_mask:0xf bound_ctrl:1
	ds_bpermute_b32 v252, v0, v251
	s_waitcnt lgkmcnt(0)
	v_add_f32_e32 v251, v251, v252
	v_fmamk_f32 v251, v251, 0x3b800000, v238
	v_mul_f32_e32 v252, 0x4f800000, v251
	v_cmp_gt_f32_e32 vcc, s24, v251
	s_nop 1
	v_cndmask_b32_e32 v251, v251, v252, vcc
	v_sqrt_f32_e32 v252, v251
	s_nop 0
	v_add_u32_e32 v249, -1, v252
	v_fma_f32 v250, -v249, v252, v251
	v_cmp_ge_f32_e64 s[6:7], 0, v250
	v_add_u32_e32 v250, 1, v252
	s_nop 0
	v_cndmask_b32_e64 v249, v252, v249, s[6:7]
	v_fma_f32 v252, -v250, v252, v251
	v_cmp_lt_f32_e64 s[6:7], 0, v252
	s_nop 1
	v_cndmask_b32_e64 v252, v249, v250, s[6:7]
	v_mul_f32_e32 v249, 0x37800000, v252
	v_cndmask_b32_e32 v252, v252, v249, vcc
	v_cmp_class_f32_e32 vcc, v251, v239
	s_nop 1
	v_cndmask_b32_e32 v251, v252, v251, vcc
	v_div_scale_f32 v252, s[2:3], v251, v251, 1.0
	v_rcp_f32_e32 v249, v252
	s_nop 0
	v_fma_f32 v250, -v252, v249, 1.0
	v_fmac_f32_e32 v249, v250, v249
	v_div_scale_f32 v250, vcc, 1.0, v251, 1.0
	v_mul_f32_e32 v253, v250, v249
	v_fma_f32 v213, -v252, v253, v250
	v_fmac_f32_e32 v253, v213, v249
	v_fma_f32 v252, -v252, v253, v250
	v_div_fmas_f32 v252, v252, v249, v253
	v_div_fixup_f32 v253, v252, v251, 1.0
	v_mul_f32_e32 v240, v240, v253
	v_mul_f32_e32 v241, v241, v253
	v_mul_f32_e32 v242, v242, v253
	v_mul_f32_e32 v243, v243, v253
	v_mul_f32_e32 v245, v245, v253
	v_mul_f32_e32 v246, v246, v253
	v_mul_f32_e32 v247, v247, v253
	v_mul_f32_e32 v248, v248, v253
	v_mul_f32_e32 v240, v224, v240
	v_mul_f32_e32 v241, v225, v241
	v_mul_f32_e32 v242, v226, v242
	v_mul_f32_e32 v243, v227, v243
	v_mul_f32_e32 v245, v228, v245
	v_mul_f32_e32 v246, v229, v246
	v_mul_f32_e32 v247, v230, v247
	v_mul_f32_e32 v248, v231, v248
	v_add_u32_e32 v249, 0xa000, v212
	v_mov_b32_dpp v232, v240 quad_perm:[1,0,3,2] row_mask:0xf bank_mask:0xf bound_ctrl:1
	v_mov_b32_dpp v233, v241 quad_perm:[1,0,3,2] row_mask:0xf bank_mask:0xf bound_ctrl:1
	v_mov_b32_dpp v234, v242 quad_perm:[1,0,3,2] row_mask:0xf bank_mask:0xf bound_ctrl:1
	v_mov_b32_dpp v235, v243 quad_perm:[1,0,3,2] row_mask:0xf bank_mask:0xf bound_ctrl:1
	v_mov_b32_dpp v2, v245 quad_perm:[1,0,3,2] row_mask:0xf bank_mask:0xf bound_ctrl:1
	v_mov_b32_dpp v3, v246 quad_perm:[1,0,3,2] row_mask:0xf bank_mask:0xf bound_ctrl:1
	v_mov_b32_dpp v5, v247 quad_perm:[1,0,3,2] row_mask:0xf bank_mask:0xf bound_ctrl:1
	v_mov_b32_dpp v151, v248 quad_perm:[1,0,3,2] row_mask:0xf bank_mask:0xf bound_ctrl:1
	v_cvt_pk_bf16_f32 v232, v240, v232
	v_cvt_pk_bf16_f32 v233, v233, v241
	v_cndmask_b32_e64 v232, v233, v232, s[60:61]
	global_store_dword v249, v232, s[58:59] offset:0 sc1
	v_cvt_pk_bf16_f32 v234, v242, v234
	v_cvt_pk_bf16_f32 v235, v235, v243
	v_cndmask_b32_e64 v234, v235, v234, s[60:61]
	global_store_dword v249, v234, s[58:59] offset:128 sc1
	v_cvt_pk_bf16_f32 v2, v245, v2
	v_cvt_pk_bf16_f32 v3, v3, v246
	v_cndmask_b32_e64 v2, v3, v2, s[60:61]
	global_store_dword v249, v2, s[58:59] offset:256 sc1
	v_cvt_pk_bf16_f32 v5, v247, v5
	v_cvt_pk_bf16_f32 v151, v151, v248
	v_cndmask_b32_e64 v5, v151, v5, s[60:61]
	global_store_dword v249, v5, s[58:59] offset:384 sc1
	s_waitcnt vmcnt(36)
	v_lshlrev_b32_e32 v250, 16, v180
	v_mul_f32_e32 v249, v137, v14
	v_fma_f32 v240, -v17, v249, v250
	v_and_b32_e32 v250, 0xffff0000, v180
	v_mul_f32_e32 v249, v121, v14
	v_fma_f32 v241, -v17, v249, v250
	v_lshlrev_b32_e32 v250, 16, v181
	v_mul_f32_e32 v249, v105, v14
	v_fma_f32 v242, -v17, v249, v250
	v_and_b32_e32 v250, 0xffff0000, v181
	v_mul_f32_e32 v249, v89, v14
	v_fma_f32 v243, -v17, v249, v250
	v_lshlrev_b32_e32 v250, 16, v182
	v_mul_f32_e32 v249, v73, v14
	v_fma_f32 v245, -v17, v249, v250
	v_and_b32_e32 v250, 0xffff0000, v182
	v_mul_f32_e32 v249, v57, v14
	v_fma_f32 v246, -v17, v249, v250
	v_lshlrev_b32_e32 v250, 16, v183
	v_mul_f32_e32 v249, v41, v14
	v_fma_f32 v247, -v17, v249, v250
	v_and_b32_e32 v250, 0xffff0000, v183
	v_mul_f32_e32 v249, v25, v14
	v_fma_f32 v248, -v17, v249, v250
	v_mul_f32_e32 v251, v241, v241
	v_fmac_f32_e32 v251, v240, v240
	v_fmac_f32_e32 v251, v242, v242
	v_fmac_f32_e32 v251, v243, v243
	v_fmac_f32_e32 v251, v245, v245
	v_fmac_f32_e32 v251, v246, v246
	v_fmac_f32_e32 v251, v247, v247
	v_fmac_f32_e32 v251, v248, v248
	s_nop 1
	v_add_f32_dpp v251, v251, v251 quad_perm:[1,0,3,2] row_mask:0xf bank_mask:0xf bound_ctrl:1
	s_nop 1
	v_add_f32_dpp v251, v251, v251 quad_perm:[2,3,0,1] row_mask:0xf bank_mask:0xf bound_ctrl:1
	s_nop 1
	v_add_f32_dpp v251, v251, v251 row_half_mirror row_mask:0xf bank_mask:0xf bound_ctrl:1
	s_nop 1
	v_add_f32_dpp v251, v251, v251 row_mirror row_mask:0xf bank_mask:0xf bound_ctrl:1
	ds_bpermute_b32 v252, v0, v251
	s_waitcnt lgkmcnt(0)
	v_add_f32_e32 v251, v251, v252
	v_fmamk_f32 v251, v251, 0x3b800000, v238
	v_mul_f32_e32 v252, 0x4f800000, v251
	v_cmp_gt_f32_e32 vcc, s24, v251
	s_nop 1
	v_cndmask_b32_e32 v251, v251, v252, vcc
	v_sqrt_f32_e32 v252, v251
	s_nop 0
	v_add_u32_e32 v249, -1, v252
	v_fma_f32 v250, -v249, v252, v251
	v_cmp_ge_f32_e64 s[6:7], 0, v250
	v_add_u32_e32 v250, 1, v252
	s_nop 0
	v_cndmask_b32_e64 v249, v252, v249, s[6:7]
	v_fma_f32 v252, -v250, v252, v251
	v_cmp_lt_f32_e64 s[6:7], 0, v252
	s_nop 1
	v_cndmask_b32_e64 v252, v249, v250, s[6:7]
	v_mul_f32_e32 v249, 0x37800000, v252
	v_cndmask_b32_e32 v252, v252, v249, vcc
	v_cmp_class_f32_e32 vcc, v251, v239
	s_nop 1
	v_cndmask_b32_e32 v251, v252, v251, vcc
	v_div_scale_f32 v252, s[2:3], v251, v251, 1.0
	v_rcp_f32_e32 v249, v252
	s_nop 0
	v_fma_f32 v250, -v252, v249, 1.0
	v_fmac_f32_e32 v249, v250, v249
	v_div_scale_f32 v250, vcc, 1.0, v251, 1.0
	v_mul_f32_e32 v253, v250, v249
	v_fma_f32 v213, -v252, v253, v250
	v_fmac_f32_e32 v253, v213, v249
	v_fma_f32 v252, -v252, v253, v250
	v_div_fmas_f32 v252, v252, v249, v253
	v_div_fixup_f32 v253, v252, v251, 1.0
	v_mul_f32_e32 v240, v240, v253
	v_mul_f32_e32 v241, v241, v253
	v_mul_f32_e32 v242, v242, v253
	v_mul_f32_e32 v243, v243, v253
	v_mul_f32_e32 v245, v245, v253
	v_mul_f32_e32 v246, v246, v253
	v_mul_f32_e32 v247, v247, v253
	v_mul_f32_e32 v248, v248, v253
	v_mul_f32_e32 v240, v224, v240
	v_mul_f32_e32 v241, v225, v241
	v_mul_f32_e32 v242, v226, v242
	v_mul_f32_e32 v243, v227, v243
	v_mul_f32_e32 v245, v228, v245
	v_mul_f32_e32 v246, v229, v246
	v_mul_f32_e32 v247, v230, v247
	v_mul_f32_e32 v248, v231, v248
	v_add_u32_e32 v249, 0xb000, v212
	v_mov_b32_dpp v232, v240 quad_perm:[1,0,3,2] row_mask:0xf bank_mask:0xf bound_ctrl:1
	v_mov_b32_dpp v233, v241 quad_perm:[1,0,3,2] row_mask:0xf bank_mask:0xf bound_ctrl:1
	v_mov_b32_dpp v234, v242 quad_perm:[1,0,3,2] row_mask:0xf bank_mask:0xf bound_ctrl:1
	v_mov_b32_dpp v235, v243 quad_perm:[1,0,3,2] row_mask:0xf bank_mask:0xf bound_ctrl:1
	v_mov_b32_dpp v2, v245 quad_perm:[1,0,3,2] row_mask:0xf bank_mask:0xf bound_ctrl:1
	v_mov_b32_dpp v3, v246 quad_perm:[1,0,3,2] row_mask:0xf bank_mask:0xf bound_ctrl:1
	v_mov_b32_dpp v5, v247 quad_perm:[1,0,3,2] row_mask:0xf bank_mask:0xf bound_ctrl:1
	v_mov_b32_dpp v151, v248 quad_perm:[1,0,3,2] row_mask:0xf bank_mask:0xf bound_ctrl:1
	v_cvt_pk_bf16_f32 v232, v240, v232
	v_cvt_pk_bf16_f32 v233, v233, v241
	v_cndmask_b32_e64 v232, v233, v232, s[60:61]
	global_store_dword v249, v232, s[58:59] offset:0 sc1
	v_cvt_pk_bf16_f32 v234, v242, v234
	v_cvt_pk_bf16_f32 v235, v235, v243
	v_cndmask_b32_e64 v234, v235, v234, s[60:61]
	global_store_dword v249, v234, s[58:59] offset:128 sc1
	v_cvt_pk_bf16_f32 v2, v245, v2
	v_cvt_pk_bf16_f32 v3, v3, v246
	v_cndmask_b32_e64 v2, v3, v2, s[60:61]
	global_store_dword v249, v2, s[58:59] offset:256 sc1
	v_cvt_pk_bf16_f32 v5, v247, v5
	v_cvt_pk_bf16_f32 v151, v151, v248
	v_cndmask_b32_e64 v5, v151, v5, s[60:61]
	global_store_dword v249, v5, s[58:59] offset:384 sc1
	s_waitcnt vmcnt(39)
	v_lshlrev_b32_e32 v250, 16, v184
	v_mul_f32_e32 v249, v138, v13
	v_fma_f32 v240, -v17, v249, v250
	v_and_b32_e32 v250, 0xffff0000, v184
	v_mul_f32_e32 v249, v122, v13
	v_fma_f32 v241, -v17, v249, v250
	v_lshlrev_b32_e32 v250, 16, v185
	v_mul_f32_e32 v249, v106, v13
	v_fma_f32 v242, -v17, v249, v250
	v_and_b32_e32 v250, 0xffff0000, v185
	v_mul_f32_e32 v249, v90, v13
	v_fma_f32 v243, -v17, v249, v250
	v_lshlrev_b32_e32 v250, 16, v186
	v_mul_f32_e32 v249, v74, v13
	v_fma_f32 v245, -v17, v249, v250
	v_and_b32_e32 v250, 0xffff0000, v186
	v_mul_f32_e32 v249, v58, v13
	v_fma_f32 v246, -v17, v249, v250
	v_lshlrev_b32_e32 v250, 16, v187
	v_mul_f32_e32 v249, v42, v13
	v_fma_f32 v247, -v17, v249, v250
	v_and_b32_e32 v250, 0xffff0000, v187
	v_mul_f32_e32 v249, v26, v13
	v_fma_f32 v248, -v17, v249, v250
	v_mul_f32_e32 v251, v241, v241
	v_fmac_f32_e32 v251, v240, v240
	v_fmac_f32_e32 v251, v242, v242
	v_fmac_f32_e32 v251, v243, v243
	v_fmac_f32_e32 v251, v245, v245
	v_fmac_f32_e32 v251, v246, v246
	v_fmac_f32_e32 v251, v247, v247
	v_fmac_f32_e32 v251, v248, v248
	s_nop 1
	v_add_f32_dpp v251, v251, v251 quad_perm:[1,0,3,2] row_mask:0xf bank_mask:0xf bound_ctrl:1
	s_nop 1
	v_add_f32_dpp v251, v251, v251 quad_perm:[2,3,0,1] row_mask:0xf bank_mask:0xf bound_ctrl:1
	s_nop 1
	v_add_f32_dpp v251, v251, v251 row_half_mirror row_mask:0xf bank_mask:0xf bound_ctrl:1
	s_nop 1
	v_add_f32_dpp v251, v251, v251 row_mirror row_mask:0xf bank_mask:0xf bound_ctrl:1
	ds_bpermute_b32 v252, v0, v251
	s_waitcnt lgkmcnt(0)
	v_add_f32_e32 v251, v251, v252
	v_fmamk_f32 v251, v251, 0x3b800000, v238
	v_mul_f32_e32 v252, 0x4f800000, v251
	v_cmp_gt_f32_e32 vcc, s24, v251
	s_nop 1
	v_cndmask_b32_e32 v251, v251, v252, vcc
	v_sqrt_f32_e32 v252, v251
	s_nop 0
	v_add_u32_e32 v249, -1, v252
	v_fma_f32 v250, -v249, v252, v251
	v_cmp_ge_f32_e64 s[6:7], 0, v250
	v_add_u32_e32 v250, 1, v252
	s_nop 0
	v_cndmask_b32_e64 v249, v252, v249, s[6:7]
	v_fma_f32 v252, -v250, v252, v251
	v_cmp_lt_f32_e64 s[6:7], 0, v252
	s_nop 1
	v_cndmask_b32_e64 v252, v249, v250, s[6:7]
	v_mul_f32_e32 v249, 0x37800000, v252
	v_cndmask_b32_e32 v252, v252, v249, vcc
	v_cmp_class_f32_e32 vcc, v251, v239
	s_nop 1
	v_cndmask_b32_e32 v251, v252, v251, vcc
	v_div_scale_f32 v252, s[2:3], v251, v251, 1.0
	v_rcp_f32_e32 v249, v252
	s_nop 0
	v_fma_f32 v250, -v252, v249, 1.0
	v_fmac_f32_e32 v249, v250, v249
	v_div_scale_f32 v250, vcc, 1.0, v251, 1.0
	v_mul_f32_e32 v253, v250, v249
	v_fma_f32 v213, -v252, v253, v250
	v_fmac_f32_e32 v253, v213, v249
	v_fma_f32 v252, -v252, v253, v250
	v_div_fmas_f32 v252, v252, v249, v253
	v_div_fixup_f32 v253, v252, v251, 1.0
	v_mul_f32_e32 v240, v240, v253
	v_mul_f32_e32 v241, v241, v253
	v_mul_f32_e32 v242, v242, v253
	v_mul_f32_e32 v243, v243, v253
	v_mul_f32_e32 v245, v245, v253
	v_mul_f32_e32 v246, v246, v253
	v_mul_f32_e32 v247, v247, v253
	v_mul_f32_e32 v248, v248, v253
	v_mul_f32_e32 v240, v224, v240
	v_mul_f32_e32 v241, v225, v241
	v_mul_f32_e32 v242, v226, v242
	v_mul_f32_e32 v243, v227, v243
	v_mul_f32_e32 v245, v228, v245
	v_mul_f32_e32 v246, v229, v246
	v_mul_f32_e32 v247, v230, v247
	v_mul_f32_e32 v248, v231, v248
	v_add_u32_e32 v249, 0x10000, v212
	v_mov_b32_dpp v232, v240 quad_perm:[1,0,3,2] row_mask:0xf bank_mask:0xf bound_ctrl:1
	v_mov_b32_dpp v233, v241 quad_perm:[1,0,3,2] row_mask:0xf bank_mask:0xf bound_ctrl:1
	v_mov_b32_dpp v234, v242 quad_perm:[1,0,3,2] row_mask:0xf bank_mask:0xf bound_ctrl:1
	v_mov_b32_dpp v235, v243 quad_perm:[1,0,3,2] row_mask:0xf bank_mask:0xf bound_ctrl:1
	v_mov_b32_dpp v2, v245 quad_perm:[1,0,3,2] row_mask:0xf bank_mask:0xf bound_ctrl:1
	v_mov_b32_dpp v3, v246 quad_perm:[1,0,3,2] row_mask:0xf bank_mask:0xf bound_ctrl:1
	v_mov_b32_dpp v5, v247 quad_perm:[1,0,3,2] row_mask:0xf bank_mask:0xf bound_ctrl:1
	v_mov_b32_dpp v151, v248 quad_perm:[1,0,3,2] row_mask:0xf bank_mask:0xf bound_ctrl:1
	v_cvt_pk_bf16_f32 v232, v240, v232
	v_cvt_pk_bf16_f32 v233, v233, v241
	v_cndmask_b32_e64 v232, v233, v232, s[60:61]
	global_store_dword v249, v232, s[58:59] offset:0 sc1
	v_cvt_pk_bf16_f32 v234, v242, v234
	v_cvt_pk_bf16_f32 v235, v235, v243
	v_cndmask_b32_e64 v234, v235, v234, s[60:61]
	global_store_dword v249, v234, s[58:59] offset:128 sc1
	v_cvt_pk_bf16_f32 v2, v245, v2
	v_cvt_pk_bf16_f32 v3, v3, v246
	v_cndmask_b32_e64 v2, v3, v2, s[60:61]
	global_store_dword v249, v2, s[58:59] offset:256 sc1
	v_cvt_pk_bf16_f32 v5, v247, v5
	v_cvt_pk_bf16_f32 v151, v151, v248
	v_cndmask_b32_e64 v5, v151, v5, s[60:61]
	global_store_dword v249, v5, s[58:59] offset:384 sc1
	s_waitcnt vmcnt(42)
	v_lshlrev_b32_e32 v250, 16, v188
	v_mul_f32_e32 v249, v139, v12
	v_fma_f32 v240, -v17, v249, v250
	v_and_b32_e32 v250, 0xffff0000, v188
	v_mul_f32_e32 v249, v123, v12
	v_fma_f32 v241, -v17, v249, v250
	v_lshlrev_b32_e32 v250, 16, v189
	v_mul_f32_e32 v249, v107, v12
	v_fma_f32 v242, -v17, v249, v250
	v_and_b32_e32 v250, 0xffff0000, v189
	v_mul_f32_e32 v249, v91, v12
	v_fma_f32 v243, -v17, v249, v250
	v_lshlrev_b32_e32 v250, 16, v190
	v_mul_f32_e32 v249, v75, v12
	v_fma_f32 v245, -v17, v249, v250
	v_and_b32_e32 v250, 0xffff0000, v190
	v_mul_f32_e32 v249, v59, v12
	v_fma_f32 v246, -v17, v249, v250
	v_lshlrev_b32_e32 v250, 16, v191
	v_mul_f32_e32 v249, v43, v12
	v_fma_f32 v247, -v17, v249, v250
	v_and_b32_e32 v250, 0xffff0000, v191
	v_mul_f32_e32 v249, v27, v12
	v_fma_f32 v248, -v17, v249, v250
	v_mul_f32_e32 v251, v241, v241
	v_fmac_f32_e32 v251, v240, v240
	v_fmac_f32_e32 v251, v242, v242
	v_fmac_f32_e32 v251, v243, v243
	v_fmac_f32_e32 v251, v245, v245
	v_fmac_f32_e32 v251, v246, v246
	v_fmac_f32_e32 v251, v247, v247
	v_fmac_f32_e32 v251, v248, v248
	s_nop 1
	v_add_f32_dpp v251, v251, v251 quad_perm:[1,0,3,2] row_mask:0xf bank_mask:0xf bound_ctrl:1
	s_nop 1
	v_add_f32_dpp v251, v251, v251 quad_perm:[2,3,0,1] row_mask:0xf bank_mask:0xf bound_ctrl:1
	s_nop 1
	v_add_f32_dpp v251, v251, v251 row_half_mirror row_mask:0xf bank_mask:0xf bound_ctrl:1
	s_nop 1
	v_add_f32_dpp v251, v251, v251 row_mirror row_mask:0xf bank_mask:0xf bound_ctrl:1
	ds_bpermute_b32 v252, v0, v251
	s_waitcnt lgkmcnt(0)
	v_add_f32_e32 v251, v251, v252
	v_fmamk_f32 v251, v251, 0x3b800000, v238
	v_mul_f32_e32 v252, 0x4f800000, v251
	v_cmp_gt_f32_e32 vcc, s24, v251
	s_nop 1
	v_cndmask_b32_e32 v251, v251, v252, vcc
	v_sqrt_f32_e32 v252, v251
	s_nop 0
	v_add_u32_e32 v249, -1, v252
	v_fma_f32 v250, -v249, v252, v251
	v_cmp_ge_f32_e64 s[6:7], 0, v250
	v_add_u32_e32 v250, 1, v252
	s_nop 0
	v_cndmask_b32_e64 v249, v252, v249, s[6:7]
	v_fma_f32 v252, -v250, v252, v251
	v_cmp_lt_f32_e64 s[6:7], 0, v252
	s_nop 1
	v_cndmask_b32_e64 v252, v249, v250, s[6:7]
	v_mul_f32_e32 v249, 0x37800000, v252
	v_cndmask_b32_e32 v252, v252, v249, vcc
	v_cmp_class_f32_e32 vcc, v251, v239
	s_nop 1
	v_cndmask_b32_e32 v251, v252, v251, vcc
	v_div_scale_f32 v252, s[2:3], v251, v251, 1.0
	v_rcp_f32_e32 v249, v252
	s_nop 0
	v_fma_f32 v250, -v252, v249, 1.0
	v_fmac_f32_e32 v249, v250, v249
	v_div_scale_f32 v250, vcc, 1.0, v251, 1.0
	v_mul_f32_e32 v253, v250, v249
	v_fma_f32 v213, -v252, v253, v250
	v_fmac_f32_e32 v253, v213, v249
	v_fma_f32 v252, -v252, v253, v250
	v_div_fmas_f32 v252, v252, v249, v253
	v_div_fixup_f32 v253, v252, v251, 1.0
	v_mul_f32_e32 v240, v240, v253
	v_mul_f32_e32 v241, v241, v253
	v_mul_f32_e32 v242, v242, v253
	v_mul_f32_e32 v243, v243, v253
	v_mul_f32_e32 v245, v245, v253
	v_mul_f32_e32 v246, v246, v253
	v_mul_f32_e32 v247, v247, v253
	v_mul_f32_e32 v248, v248, v253
	v_mul_f32_e32 v240, v224, v240
	v_mul_f32_e32 v241, v225, v241
	v_mul_f32_e32 v242, v226, v242
	v_mul_f32_e32 v243, v227, v243
	v_mul_f32_e32 v245, v228, v245
	v_mul_f32_e32 v246, v229, v246
	v_mul_f32_e32 v247, v230, v247
	v_mul_f32_e32 v248, v231, v248
	v_add_u32_e32 v249, 0x11000, v212
	v_mov_b32_dpp v232, v240 quad_perm:[1,0,3,2] row_mask:0xf bank_mask:0xf bound_ctrl:1
	v_mov_b32_dpp v233, v241 quad_perm:[1,0,3,2] row_mask:0xf bank_mask:0xf bound_ctrl:1
	v_mov_b32_dpp v234, v242 quad_perm:[1,0,3,2] row_mask:0xf bank_mask:0xf bound_ctrl:1
	v_mov_b32_dpp v235, v243 quad_perm:[1,0,3,2] row_mask:0xf bank_mask:0xf bound_ctrl:1
	v_mov_b32_dpp v2, v245 quad_perm:[1,0,3,2] row_mask:0xf bank_mask:0xf bound_ctrl:1
	v_mov_b32_dpp v3, v246 quad_perm:[1,0,3,2] row_mask:0xf bank_mask:0xf bound_ctrl:1
	v_mov_b32_dpp v5, v247 quad_perm:[1,0,3,2] row_mask:0xf bank_mask:0xf bound_ctrl:1
	v_mov_b32_dpp v151, v248 quad_perm:[1,0,3,2] row_mask:0xf bank_mask:0xf bound_ctrl:1
	v_cvt_pk_bf16_f32 v232, v240, v232
	v_cvt_pk_bf16_f32 v233, v233, v241
	v_cndmask_b32_e64 v232, v233, v232, s[60:61]
	global_store_dword v249, v232, s[58:59] offset:0 sc1
	v_cvt_pk_bf16_f32 v234, v242, v234
	v_cvt_pk_bf16_f32 v235, v235, v243
	v_cndmask_b32_e64 v234, v235, v234, s[60:61]
	global_store_dword v249, v234, s[58:59] offset:128 sc1
	v_cvt_pk_bf16_f32 v2, v245, v2
	v_cvt_pk_bf16_f32 v3, v3, v246
	v_cndmask_b32_e64 v2, v3, v2, s[60:61]
	global_store_dword v249, v2, s[58:59] offset:256 sc1
	v_cvt_pk_bf16_f32 v5, v247, v5
	v_cvt_pk_bf16_f32 v151, v151, v248
	v_cndmask_b32_e64 v5, v151, v5, s[60:61]
	global_store_dword v249, v5, s[58:59] offset:384 sc1
	s_waitcnt vmcnt(45)
	v_lshlrev_b32_e32 v250, 16, v192
	v_mul_f32_e32 v249, v140, v11
	v_fma_f32 v240, -v17, v249, v250
	v_and_b32_e32 v250, 0xffff0000, v192
	v_mul_f32_e32 v249, v124, v11
	v_fma_f32 v241, -v17, v249, v250
	v_lshlrev_b32_e32 v250, 16, v193
	v_mul_f32_e32 v249, v108, v11
	v_fma_f32 v242, -v17, v249, v250
	v_and_b32_e32 v250, 0xffff0000, v193
	v_mul_f32_e32 v249, v92, v11
	v_fma_f32 v243, -v17, v249, v250
	v_lshlrev_b32_e32 v250, 16, v194
	v_mul_f32_e32 v249, v76, v11
	v_fma_f32 v245, -v17, v249, v250
	v_and_b32_e32 v250, 0xffff0000, v194
	v_mul_f32_e32 v249, v60, v11
	v_fma_f32 v246, -v17, v249, v250
	v_lshlrev_b32_e32 v250, 16, v195
	v_mul_f32_e32 v249, v44, v11
	v_fma_f32 v247, -v17, v249, v250
	v_and_b32_e32 v250, 0xffff0000, v195
	v_mul_f32_e32 v249, v28, v11
	v_fma_f32 v248, -v17, v249, v250
	v_mul_f32_e32 v251, v241, v241
	v_fmac_f32_e32 v251, v240, v240
	v_fmac_f32_e32 v251, v242, v242
	v_fmac_f32_e32 v251, v243, v243
	v_fmac_f32_e32 v251, v245, v245
	v_fmac_f32_e32 v251, v246, v246
	v_fmac_f32_e32 v251, v247, v247
	v_fmac_f32_e32 v251, v248, v248
	s_nop 1
	v_add_f32_dpp v251, v251, v251 quad_perm:[1,0,3,2] row_mask:0xf bank_mask:0xf bound_ctrl:1
	s_nop 1
	v_add_f32_dpp v251, v251, v251 quad_perm:[2,3,0,1] row_mask:0xf bank_mask:0xf bound_ctrl:1
	s_nop 1
	v_add_f32_dpp v251, v251, v251 row_half_mirror row_mask:0xf bank_mask:0xf bound_ctrl:1
	s_nop 1
	v_add_f32_dpp v251, v251, v251 row_mirror row_mask:0xf bank_mask:0xf bound_ctrl:1
	ds_bpermute_b32 v252, v0, v251
	s_waitcnt lgkmcnt(0)
	v_add_f32_e32 v251, v251, v252
	v_fmamk_f32 v251, v251, 0x3b800000, v238
	v_mul_f32_e32 v252, 0x4f800000, v251
	v_cmp_gt_f32_e32 vcc, s24, v251
	s_nop 1
	v_cndmask_b32_e32 v251, v251, v252, vcc
	v_sqrt_f32_e32 v252, v251
	s_nop 0
	v_add_u32_e32 v249, -1, v252
	v_fma_f32 v250, -v249, v252, v251
	v_cmp_ge_f32_e64 s[6:7], 0, v250
	v_add_u32_e32 v250, 1, v252
	s_nop 0
	v_cndmask_b32_e64 v249, v252, v249, s[6:7]
	v_fma_f32 v252, -v250, v252, v251
	v_cmp_lt_f32_e64 s[6:7], 0, v252
	s_nop 1
	v_cndmask_b32_e64 v252, v249, v250, s[6:7]
	v_mul_f32_e32 v249, 0x37800000, v252
	v_cndmask_b32_e32 v252, v252, v249, vcc
	v_cmp_class_f32_e32 vcc, v251, v239
	s_nop 1
	v_cndmask_b32_e32 v251, v252, v251, vcc
	v_div_scale_f32 v252, s[2:3], v251, v251, 1.0
	v_rcp_f32_e32 v249, v252
	s_nop 0
	v_fma_f32 v250, -v252, v249, 1.0
	v_fmac_f32_e32 v249, v250, v249
	v_div_scale_f32 v250, vcc, 1.0, v251, 1.0
	v_mul_f32_e32 v253, v250, v249
	v_fma_f32 v213, -v252, v253, v250
	v_fmac_f32_e32 v253, v213, v249
	v_fma_f32 v252, -v252, v253, v250
	v_div_fmas_f32 v252, v252, v249, v253
	v_div_fixup_f32 v253, v252, v251, 1.0
	v_mul_f32_e32 v240, v240, v253
	v_mul_f32_e32 v241, v241, v253
	v_mul_f32_e32 v242, v242, v253
	v_mul_f32_e32 v243, v243, v253
	v_mul_f32_e32 v245, v245, v253
	v_mul_f32_e32 v246, v246, v253
	v_mul_f32_e32 v247, v247, v253
	v_mul_f32_e32 v248, v248, v253
	v_mul_f32_e32 v240, v224, v240
	v_mul_f32_e32 v241, v225, v241
	v_mul_f32_e32 v242, v226, v242
	v_mul_f32_e32 v243, v227, v243
	v_mul_f32_e32 v245, v228, v245
	v_mul_f32_e32 v246, v229, v246
	v_mul_f32_e32 v247, v230, v247
	v_mul_f32_e32 v248, v231, v248
	v_add_u32_e32 v249, 0x12000, v212
	v_mov_b32_dpp v232, v240 quad_perm:[1,0,3,2] row_mask:0xf bank_mask:0xf bound_ctrl:1
	v_mov_b32_dpp v233, v241 quad_perm:[1,0,3,2] row_mask:0xf bank_mask:0xf bound_ctrl:1
	v_mov_b32_dpp v234, v242 quad_perm:[1,0,3,2] row_mask:0xf bank_mask:0xf bound_ctrl:1
	v_mov_b32_dpp v235, v243 quad_perm:[1,0,3,2] row_mask:0xf bank_mask:0xf bound_ctrl:1
	v_mov_b32_dpp v2, v245 quad_perm:[1,0,3,2] row_mask:0xf bank_mask:0xf bound_ctrl:1
	v_mov_b32_dpp v3, v246 quad_perm:[1,0,3,2] row_mask:0xf bank_mask:0xf bound_ctrl:1
	v_mov_b32_dpp v5, v247 quad_perm:[1,0,3,2] row_mask:0xf bank_mask:0xf bound_ctrl:1
	v_mov_b32_dpp v151, v248 quad_perm:[1,0,3,2] row_mask:0xf bank_mask:0xf bound_ctrl:1
	v_cvt_pk_bf16_f32 v232, v240, v232
	v_cvt_pk_bf16_f32 v233, v233, v241
	v_cndmask_b32_e64 v232, v233, v232, s[60:61]
	global_store_dword v249, v232, s[58:59] offset:0 sc1
	v_cvt_pk_bf16_f32 v234, v242, v234
	v_cvt_pk_bf16_f32 v235, v235, v243
	v_cndmask_b32_e64 v234, v235, v234, s[60:61]
	global_store_dword v249, v234, s[58:59] offset:128 sc1
	v_cvt_pk_bf16_f32 v2, v245, v2
	v_cvt_pk_bf16_f32 v3, v3, v246
	v_cndmask_b32_e64 v2, v3, v2, s[60:61]
	global_store_dword v249, v2, s[58:59] offset:256 sc1
	v_cvt_pk_bf16_f32 v5, v247, v5
	v_cvt_pk_bf16_f32 v151, v151, v248
	v_cndmask_b32_e64 v5, v151, v5, s[60:61]
	global_store_dword v249, v5, s[58:59] offset:384 sc1
	s_waitcnt vmcnt(48)
	v_lshlrev_b32_e32 v250, 16, v196
	v_mul_f32_e32 v249, v141, v10
	v_fma_f32 v240, -v17, v249, v250
	v_and_b32_e32 v250, 0xffff0000, v196
	v_mul_f32_e32 v249, v125, v10
	v_fma_f32 v241, -v17, v249, v250
	v_lshlrev_b32_e32 v250, 16, v197
	v_mul_f32_e32 v249, v109, v10
	v_fma_f32 v242, -v17, v249, v250
	v_and_b32_e32 v250, 0xffff0000, v197
	v_mul_f32_e32 v249, v93, v10
	v_fma_f32 v243, -v17, v249, v250
	v_lshlrev_b32_e32 v250, 16, v198
	v_mul_f32_e32 v249, v77, v10
	v_fma_f32 v245, -v17, v249, v250
	v_and_b32_e32 v250, 0xffff0000, v198
	v_mul_f32_e32 v249, v61, v10
	v_fma_f32 v246, -v17, v249, v250
	v_lshlrev_b32_e32 v250, 16, v199
	v_mul_f32_e32 v249, v45, v10
	v_fma_f32 v247, -v17, v249, v250
	v_and_b32_e32 v250, 0xffff0000, v199
	v_mul_f32_e32 v249, v29, v10
	v_fma_f32 v248, -v17, v249, v250
	v_mul_f32_e32 v251, v241, v241
	v_fmac_f32_e32 v251, v240, v240
	v_fmac_f32_e32 v251, v242, v242
	v_fmac_f32_e32 v251, v243, v243
	v_fmac_f32_e32 v251, v245, v245
	v_fmac_f32_e32 v251, v246, v246
	v_fmac_f32_e32 v251, v247, v247
	v_fmac_f32_e32 v251, v248, v248
	s_nop 1
	v_add_f32_dpp v251, v251, v251 quad_perm:[1,0,3,2] row_mask:0xf bank_mask:0xf bound_ctrl:1
	s_nop 1
	v_add_f32_dpp v251, v251, v251 quad_perm:[2,3,0,1] row_mask:0xf bank_mask:0xf bound_ctrl:1
	s_nop 1
	v_add_f32_dpp v251, v251, v251 row_half_mirror row_mask:0xf bank_mask:0xf bound_ctrl:1
	s_nop 1
	v_add_f32_dpp v251, v251, v251 row_mirror row_mask:0xf bank_mask:0xf bound_ctrl:1
	ds_bpermute_b32 v252, v0, v251
	s_waitcnt lgkmcnt(0)
	v_add_f32_e32 v251, v251, v252
	v_fmamk_f32 v251, v251, 0x3b800000, v238
	v_mul_f32_e32 v252, 0x4f800000, v251
	v_cmp_gt_f32_e32 vcc, s24, v251
	s_nop 1
	v_cndmask_b32_e32 v251, v251, v252, vcc
	v_sqrt_f32_e32 v252, v251
	s_nop 0
	v_add_u32_e32 v249, -1, v252
	v_fma_f32 v250, -v249, v252, v251
	v_cmp_ge_f32_e64 s[6:7], 0, v250
	v_add_u32_e32 v250, 1, v252
	s_nop 0
	v_cndmask_b32_e64 v249, v252, v249, s[6:7]
	v_fma_f32 v252, -v250, v252, v251
	v_cmp_lt_f32_e64 s[6:7], 0, v252
	s_nop 1
	v_cndmask_b32_e64 v252, v249, v250, s[6:7]
	v_mul_f32_e32 v249, 0x37800000, v252
	v_cndmask_b32_e32 v252, v252, v249, vcc
	v_cmp_class_f32_e32 vcc, v251, v239
	s_nop 1
	v_cndmask_b32_e32 v251, v252, v251, vcc
	v_div_scale_f32 v252, s[2:3], v251, v251, 1.0
	v_rcp_f32_e32 v249, v252
	s_nop 0
	v_fma_f32 v250, -v252, v249, 1.0
	v_fmac_f32_e32 v249, v250, v249
	v_div_scale_f32 v250, vcc, 1.0, v251, 1.0
	v_mul_f32_e32 v253, v250, v249
	v_fma_f32 v213, -v252, v253, v250
	v_fmac_f32_e32 v253, v213, v249
	v_fma_f32 v252, -v252, v253, v250
	v_div_fmas_f32 v252, v252, v249, v253
	v_div_fixup_f32 v253, v252, v251, 1.0
	v_mul_f32_e32 v240, v240, v253
	v_mul_f32_e32 v241, v241, v253
	v_mul_f32_e32 v242, v242, v253
	v_mul_f32_e32 v243, v243, v253
	v_mul_f32_e32 v245, v245, v253
	v_mul_f32_e32 v246, v246, v253
	v_mul_f32_e32 v247, v247, v253
	v_mul_f32_e32 v248, v248, v253
	v_mul_f32_e32 v240, v224, v240
	v_mul_f32_e32 v241, v225, v241
	v_mul_f32_e32 v242, v226, v242
	v_mul_f32_e32 v243, v227, v243
	v_mul_f32_e32 v245, v228, v245
	v_mul_f32_e32 v246, v229, v246
	v_mul_f32_e32 v247, v230, v247
	v_mul_f32_e32 v248, v231, v248
	v_add_u32_e32 v249, 0x13000, v212
	v_mov_b32_dpp v232, v240 quad_perm:[1,0,3,2] row_mask:0xf bank_mask:0xf bound_ctrl:1
	v_mov_b32_dpp v233, v241 quad_perm:[1,0,3,2] row_mask:0xf bank_mask:0xf bound_ctrl:1
	v_mov_b32_dpp v234, v242 quad_perm:[1,0,3,2] row_mask:0xf bank_mask:0xf bound_ctrl:1
	v_mov_b32_dpp v235, v243 quad_perm:[1,0,3,2] row_mask:0xf bank_mask:0xf bound_ctrl:1
	v_mov_b32_dpp v2, v245 quad_perm:[1,0,3,2] row_mask:0xf bank_mask:0xf bound_ctrl:1
	v_mov_b32_dpp v3, v246 quad_perm:[1,0,3,2] row_mask:0xf bank_mask:0xf bound_ctrl:1
	v_mov_b32_dpp v5, v247 quad_perm:[1,0,3,2] row_mask:0xf bank_mask:0xf bound_ctrl:1
	v_mov_b32_dpp v151, v248 quad_perm:[1,0,3,2] row_mask:0xf bank_mask:0xf bound_ctrl:1
	v_cvt_pk_bf16_f32 v232, v240, v232
	v_cvt_pk_bf16_f32 v233, v233, v241
	v_cndmask_b32_e64 v232, v233, v232, s[60:61]
	global_store_dword v249, v232, s[58:59] offset:0 sc1
	v_cvt_pk_bf16_f32 v234, v242, v234
	v_cvt_pk_bf16_f32 v235, v235, v243
	v_cndmask_b32_e64 v234, v235, v234, s[60:61]
	global_store_dword v249, v234, s[58:59] offset:128 sc1
	v_cvt_pk_bf16_f32 v2, v245, v2
	v_cvt_pk_bf16_f32 v3, v3, v246
	v_cndmask_b32_e64 v2, v3, v2, s[60:61]
	global_store_dword v249, v2, s[58:59] offset:256 sc1
	v_cvt_pk_bf16_f32 v5, v247, v5
	v_cvt_pk_bf16_f32 v151, v151, v248
	v_cndmask_b32_e64 v5, v151, v5, s[60:61]
	global_store_dword v249, v5, s[58:59] offset:384 sc1
	s_waitcnt vmcnt(51)
	v_lshlrev_b32_e32 v250, 16, v200
	v_mul_f32_e32 v249, v142, v9
	v_fma_f32 v240, -v17, v249, v250
	v_and_b32_e32 v250, 0xffff0000, v200
	v_mul_f32_e32 v249, v126, v9
	v_fma_f32 v241, -v17, v249, v250
	v_lshlrev_b32_e32 v250, 16, v201
	v_mul_f32_e32 v249, v110, v9
	v_fma_f32 v242, -v17, v249, v250
	v_and_b32_e32 v250, 0xffff0000, v201
	v_mul_f32_e32 v249, v94, v9
	v_fma_f32 v243, -v17, v249, v250
	v_lshlrev_b32_e32 v250, 16, v202
	v_mul_f32_e32 v249, v78, v9
	v_fma_f32 v245, -v17, v249, v250
	v_and_b32_e32 v250, 0xffff0000, v202
	v_mul_f32_e32 v249, v62, v9
	v_fma_f32 v246, -v17, v249, v250
	v_lshlrev_b32_e32 v250, 16, v203
	v_mul_f32_e32 v249, v46, v9
	v_fma_f32 v247, -v17, v249, v250
	v_and_b32_e32 v250, 0xffff0000, v203
	v_mul_f32_e32 v249, v30, v9
	v_fma_f32 v248, -v17, v249, v250
	v_mul_f32_e32 v251, v241, v241
	v_fmac_f32_e32 v251, v240, v240
	v_fmac_f32_e32 v251, v242, v242
	v_fmac_f32_e32 v251, v243, v243
	v_fmac_f32_e32 v251, v245, v245
	v_fmac_f32_e32 v251, v246, v246
	v_fmac_f32_e32 v251, v247, v247
	v_fmac_f32_e32 v251, v248, v248
	s_nop 1
	v_add_f32_dpp v251, v251, v251 quad_perm:[1,0,3,2] row_mask:0xf bank_mask:0xf bound_ctrl:1
	s_nop 1
	v_add_f32_dpp v251, v251, v251 quad_perm:[2,3,0,1] row_mask:0xf bank_mask:0xf bound_ctrl:1
	s_nop 1
	v_add_f32_dpp v251, v251, v251 row_half_mirror row_mask:0xf bank_mask:0xf bound_ctrl:1
	s_nop 1
	v_add_f32_dpp v251, v251, v251 row_mirror row_mask:0xf bank_mask:0xf bound_ctrl:1
	ds_bpermute_b32 v252, v0, v251
	s_waitcnt lgkmcnt(0)
	v_add_f32_e32 v251, v251, v252
	v_fmamk_f32 v251, v251, 0x3b800000, v238
	v_mul_f32_e32 v252, 0x4f800000, v251
	v_cmp_gt_f32_e32 vcc, s24, v251
	s_nop 1
	v_cndmask_b32_e32 v251, v251, v252, vcc
	v_sqrt_f32_e32 v252, v251
	s_nop 0
	v_add_u32_e32 v249, -1, v252
	v_fma_f32 v250, -v249, v252, v251
	v_cmp_ge_f32_e64 s[6:7], 0, v250
	v_add_u32_e32 v250, 1, v252
	s_nop 0
	v_cndmask_b32_e64 v249, v252, v249, s[6:7]
	v_fma_f32 v252, -v250, v252, v251
	v_cmp_lt_f32_e64 s[6:7], 0, v252
	s_nop 1
	v_cndmask_b32_e64 v252, v249, v250, s[6:7]
	v_mul_f32_e32 v249, 0x37800000, v252
	v_cndmask_b32_e32 v252, v252, v249, vcc
	v_cmp_class_f32_e32 vcc, v251, v239
	s_nop 1
	v_cndmask_b32_e32 v251, v252, v251, vcc
	v_div_scale_f32 v252, s[2:3], v251, v251, 1.0
	v_rcp_f32_e32 v249, v252
	s_nop 0
	v_fma_f32 v250, -v252, v249, 1.0
	v_fmac_f32_e32 v249, v250, v249
	v_div_scale_f32 v250, vcc, 1.0, v251, 1.0
	v_mul_f32_e32 v253, v250, v249
	v_fma_f32 v213, -v252, v253, v250
	v_fmac_f32_e32 v253, v213, v249
	v_fma_f32 v252, -v252, v253, v250
	v_div_fmas_f32 v252, v252, v249, v253
	v_div_fixup_f32 v253, v252, v251, 1.0
	v_mul_f32_e32 v240, v240, v253
	v_mul_f32_e32 v241, v241, v253
	v_mul_f32_e32 v242, v242, v253
	v_mul_f32_e32 v243, v243, v253
	v_mul_f32_e32 v245, v245, v253
	v_mul_f32_e32 v246, v246, v253
	v_mul_f32_e32 v247, v247, v253
	v_mul_f32_e32 v248, v248, v253
	v_mul_f32_e32 v240, v224, v240
	v_mul_f32_e32 v241, v225, v241
	v_mul_f32_e32 v242, v226, v242
	v_mul_f32_e32 v243, v227, v243
	v_mul_f32_e32 v245, v228, v245
	v_mul_f32_e32 v246, v229, v246
	v_mul_f32_e32 v247, v230, v247
	v_mul_f32_e32 v248, v231, v248
	v_add_u32_e32 v249, 0x18000, v212
	v_mov_b32_dpp v232, v240 quad_perm:[1,0,3,2] row_mask:0xf bank_mask:0xf bound_ctrl:1
	v_mov_b32_dpp v233, v241 quad_perm:[1,0,3,2] row_mask:0xf bank_mask:0xf bound_ctrl:1
	v_mov_b32_dpp v234, v242 quad_perm:[1,0,3,2] row_mask:0xf bank_mask:0xf bound_ctrl:1
	v_mov_b32_dpp v235, v243 quad_perm:[1,0,3,2] row_mask:0xf bank_mask:0xf bound_ctrl:1
	v_mov_b32_dpp v2, v245 quad_perm:[1,0,3,2] row_mask:0xf bank_mask:0xf bound_ctrl:1
	v_mov_b32_dpp v3, v246 quad_perm:[1,0,3,2] row_mask:0xf bank_mask:0xf bound_ctrl:1
	v_mov_b32_dpp v5, v247 quad_perm:[1,0,3,2] row_mask:0xf bank_mask:0xf bound_ctrl:1
	v_mov_b32_dpp v151, v248 quad_perm:[1,0,3,2] row_mask:0xf bank_mask:0xf bound_ctrl:1
	v_cvt_pk_bf16_f32 v232, v240, v232
	v_cvt_pk_bf16_f32 v233, v233, v241
	v_cndmask_b32_e64 v232, v233, v232, s[60:61]
	global_store_dword v249, v232, s[58:59] offset:0 sc1
	v_cvt_pk_bf16_f32 v234, v242, v234
	v_cvt_pk_bf16_f32 v235, v235, v243
	v_cndmask_b32_e64 v234, v235, v234, s[60:61]
	global_store_dword v249, v234, s[58:59] offset:128 sc1
	v_cvt_pk_bf16_f32 v2, v245, v2
	v_cvt_pk_bf16_f32 v3, v3, v246
	v_cndmask_b32_e64 v2, v3, v2, s[60:61]
	global_store_dword v249, v2, s[58:59] offset:256 sc1
	v_cvt_pk_bf16_f32 v5, v247, v5
	v_cvt_pk_bf16_f32 v151, v151, v248
	v_cndmask_b32_e64 v5, v151, v5, s[60:61]
	global_store_dword v249, v5, s[58:59] offset:384 sc1
	s_waitcnt vmcnt(54)
	v_lshlrev_b32_e32 v250, 16, v204
	v_mul_f32_e32 v249, v143, v8
	v_fma_f32 v240, -v17, v249, v250
	v_and_b32_e32 v250, 0xffff0000, v204
	v_mul_f32_e32 v249, v127, v8
	v_fma_f32 v241, -v17, v249, v250
	v_lshlrev_b32_e32 v250, 16, v205
	v_mul_f32_e32 v249, v111, v8
	v_fma_f32 v242, -v17, v249, v250
	v_and_b32_e32 v250, 0xffff0000, v205
	v_mul_f32_e32 v249, v95, v8
	v_fma_f32 v243, -v17, v249, v250
	v_lshlrev_b32_e32 v250, 16, v206
	v_mul_f32_e32 v249, v79, v8
	v_fma_f32 v245, -v17, v249, v250
	v_and_b32_e32 v250, 0xffff0000, v206
	v_mul_f32_e32 v249, v63, v8
	v_fma_f32 v246, -v17, v249, v250
	v_lshlrev_b32_e32 v250, 16, v207
	v_mul_f32_e32 v249, v47, v8
	v_fma_f32 v247, -v17, v249, v250
	v_and_b32_e32 v250, 0xffff0000, v207
	v_mul_f32_e32 v249, v31, v8
	v_fma_f32 v248, -v17, v249, v250
	v_mul_f32_e32 v251, v241, v241
	v_fmac_f32_e32 v251, v240, v240
	v_fmac_f32_e32 v251, v242, v242
	v_fmac_f32_e32 v251, v243, v243
	v_fmac_f32_e32 v251, v245, v245
	v_fmac_f32_e32 v251, v246, v246
	v_fmac_f32_e32 v251, v247, v247
	v_fmac_f32_e32 v251, v248, v248
	s_nop 1
	v_add_f32_dpp v251, v251, v251 quad_perm:[1,0,3,2] row_mask:0xf bank_mask:0xf bound_ctrl:1
	s_nop 1
	v_add_f32_dpp v251, v251, v251 quad_perm:[2,3,0,1] row_mask:0xf bank_mask:0xf bound_ctrl:1
	s_nop 1
	v_add_f32_dpp v251, v251, v251 row_half_mirror row_mask:0xf bank_mask:0xf bound_ctrl:1
	s_nop 1
	v_add_f32_dpp v251, v251, v251 row_mirror row_mask:0xf bank_mask:0xf bound_ctrl:1
	ds_bpermute_b32 v252, v0, v251
	s_waitcnt lgkmcnt(0)
	v_add_f32_e32 v251, v251, v252
	v_fmamk_f32 v251, v251, 0x3b800000, v238
	v_mul_f32_e32 v252, 0x4f800000, v251
	v_cmp_gt_f32_e32 vcc, s24, v251
	s_nop 1
	v_cndmask_b32_e32 v251, v251, v252, vcc
	v_sqrt_f32_e32 v252, v251
	s_nop 0
	v_add_u32_e32 v249, -1, v252
	v_fma_f32 v250, -v249, v252, v251
	v_cmp_ge_f32_e64 s[6:7], 0, v250
	v_add_u32_e32 v250, 1, v252
	s_nop 0
	v_cndmask_b32_e64 v249, v252, v249, s[6:7]
	v_fma_f32 v252, -v250, v252, v251
	v_cmp_lt_f32_e64 s[6:7], 0, v252
	s_nop 1
	v_cndmask_b32_e64 v252, v249, v250, s[6:7]
	v_mul_f32_e32 v249, 0x37800000, v252
	v_cndmask_b32_e32 v252, v252, v249, vcc
	v_cmp_class_f32_e32 vcc, v251, v239
	s_nop 1
	v_cndmask_b32_e32 v251, v252, v251, vcc
	v_div_scale_f32 v252, s[2:3], v251, v251, 1.0
	v_rcp_f32_e32 v249, v252
	s_nop 0
	v_fma_f32 v250, -v252, v249, 1.0
	v_fmac_f32_e32 v249, v250, v249
	v_div_scale_f32 v250, vcc, 1.0, v251, 1.0
	v_mul_f32_e32 v253, v250, v249
	v_fma_f32 v213, -v252, v253, v250
	v_fmac_f32_e32 v253, v213, v249
	v_fma_f32 v252, -v252, v253, v250
	v_div_fmas_f32 v252, v252, v249, v253
	v_div_fixup_f32 v253, v252, v251, 1.0
	v_mul_f32_e32 v240, v240, v253
	v_mul_f32_e32 v241, v241, v253
	v_mul_f32_e32 v242, v242, v253
	v_mul_f32_e32 v243, v243, v253
	v_mul_f32_e32 v245, v245, v253
	v_mul_f32_e32 v246, v246, v253
	v_mul_f32_e32 v247, v247, v253
	v_mul_f32_e32 v248, v248, v253
	v_mul_f32_e32 v240, v224, v240
	v_mul_f32_e32 v241, v225, v241
	v_mul_f32_e32 v242, v226, v242
	v_mul_f32_e32 v243, v227, v243
	v_mul_f32_e32 v245, v228, v245
	v_mul_f32_e32 v246, v229, v246
	v_mul_f32_e32 v247, v230, v247
	v_mul_f32_e32 v248, v231, v248
	v_add_u32_e32 v249, 0x19000, v212
	v_mov_b32_dpp v232, v240 quad_perm:[1,0,3,2] row_mask:0xf bank_mask:0xf bound_ctrl:1
	v_mov_b32_dpp v233, v241 quad_perm:[1,0,3,2] row_mask:0xf bank_mask:0xf bound_ctrl:1
	v_mov_b32_dpp v234, v242 quad_perm:[1,0,3,2] row_mask:0xf bank_mask:0xf bound_ctrl:1
	v_mov_b32_dpp v235, v243 quad_perm:[1,0,3,2] row_mask:0xf bank_mask:0xf bound_ctrl:1
	v_mov_b32_dpp v2, v245 quad_perm:[1,0,3,2] row_mask:0xf bank_mask:0xf bound_ctrl:1
	v_mov_b32_dpp v3, v246 quad_perm:[1,0,3,2] row_mask:0xf bank_mask:0xf bound_ctrl:1
	v_mov_b32_dpp v5, v247 quad_perm:[1,0,3,2] row_mask:0xf bank_mask:0xf bound_ctrl:1
	v_mov_b32_dpp v151, v248 quad_perm:[1,0,3,2] row_mask:0xf bank_mask:0xf bound_ctrl:1
	v_cvt_pk_bf16_f32 v232, v240, v232
	v_cvt_pk_bf16_f32 v233, v233, v241
	v_cndmask_b32_e64 v232, v233, v232, s[60:61]
	global_store_dword v249, v232, s[58:59] offset:0 sc1
	v_cvt_pk_bf16_f32 v234, v242, v234
	v_cvt_pk_bf16_f32 v235, v235, v243
	v_cndmask_b32_e64 v234, v235, v234, s[60:61]
	global_store_dword v249, v234, s[58:59] offset:128 sc1
	v_cvt_pk_bf16_f32 v2, v245, v2
	v_cvt_pk_bf16_f32 v3, v3, v246
	v_cndmask_b32_e64 v2, v3, v2, s[60:61]
	global_store_dword v249, v2, s[58:59] offset:256 sc1
	v_cvt_pk_bf16_f32 v5, v247, v5
	v_cvt_pk_bf16_f32 v151, v151, v248
	v_cndmask_b32_e64 v5, v151, v5, s[60:61]
	global_store_dword v249, v5, s[58:59] offset:384 sc1
	s_waitcnt vmcnt(57)
	v_lshlrev_b32_e32 v250, 16, v216
	v_mul_f32_e32 v249, v144, v7
	v_fma_f32 v240, -v17, v249, v250
	v_and_b32_e32 v250, 0xffff0000, v216
	v_mul_f32_e32 v249, v128, v7
	v_fma_f32 v241, -v17, v249, v250
	v_lshlrev_b32_e32 v250, 16, v217
	v_mul_f32_e32 v249, v112, v7
	v_fma_f32 v242, -v17, v249, v250
	v_and_b32_e32 v250, 0xffff0000, v217
	v_mul_f32_e32 v249, v96, v7
	v_fma_f32 v243, -v17, v249, v250
	v_lshlrev_b32_e32 v250, 16, v218
	v_mul_f32_e32 v249, v80, v7
	v_fma_f32 v245, -v17, v249, v250
	v_and_b32_e32 v250, 0xffff0000, v218
	v_mul_f32_e32 v249, v64, v7
	v_fma_f32 v246, -v17, v249, v250
	v_lshlrev_b32_e32 v250, 16, v219
	v_mul_f32_e32 v249, v48, v7
	v_fma_f32 v247, -v17, v249, v250
	v_and_b32_e32 v250, 0xffff0000, v219
	v_mul_f32_e32 v249, v32, v7
	v_fma_f32 v248, -v17, v249, v250
	v_mul_f32_e32 v251, v241, v241
	v_fmac_f32_e32 v251, v240, v240
	v_fmac_f32_e32 v251, v242, v242
	v_fmac_f32_e32 v251, v243, v243
	v_fmac_f32_e32 v251, v245, v245
	v_fmac_f32_e32 v251, v246, v246
	v_fmac_f32_e32 v251, v247, v247
	v_fmac_f32_e32 v251, v248, v248
	s_nop 1
	v_add_f32_dpp v251, v251, v251 quad_perm:[1,0,3,2] row_mask:0xf bank_mask:0xf bound_ctrl:1
	s_nop 1
	v_add_f32_dpp v251, v251, v251 quad_perm:[2,3,0,1] row_mask:0xf bank_mask:0xf bound_ctrl:1
	s_nop 1
	v_add_f32_dpp v251, v251, v251 row_half_mirror row_mask:0xf bank_mask:0xf bound_ctrl:1
	s_nop 1
	v_add_f32_dpp v251, v251, v251 row_mirror row_mask:0xf bank_mask:0xf bound_ctrl:1
	ds_bpermute_b32 v252, v0, v251
	s_waitcnt lgkmcnt(0)
	v_add_f32_e32 v251, v251, v252
	v_fmamk_f32 v251, v251, 0x3b800000, v238
	v_mul_f32_e32 v252, 0x4f800000, v251
	v_cmp_gt_f32_e32 vcc, s24, v251
	s_nop 1
	v_cndmask_b32_e32 v251, v251, v252, vcc
	v_sqrt_f32_e32 v252, v251
	s_nop 0
	v_add_u32_e32 v249, -1, v252
	v_fma_f32 v250, -v249, v252, v251
	v_cmp_ge_f32_e64 s[6:7], 0, v250
	v_add_u32_e32 v250, 1, v252
	s_nop 0
	v_cndmask_b32_e64 v249, v252, v249, s[6:7]
	v_fma_f32 v252, -v250, v252, v251
	v_cmp_lt_f32_e64 s[6:7], 0, v252
	s_nop 1
	v_cndmask_b32_e64 v252, v249, v250, s[6:7]
	v_mul_f32_e32 v249, 0x37800000, v252
	v_cndmask_b32_e32 v252, v252, v249, vcc
	v_cmp_class_f32_e32 vcc, v251, v239
	s_nop 1
	v_cndmask_b32_e32 v251, v252, v251, vcc
	v_div_scale_f32 v252, s[2:3], v251, v251, 1.0
	v_rcp_f32_e32 v249, v252
	s_nop 0
	v_fma_f32 v250, -v252, v249, 1.0
	v_fmac_f32_e32 v249, v250, v249
	v_div_scale_f32 v250, vcc, 1.0, v251, 1.0
	v_mul_f32_e32 v253, v250, v249
	v_fma_f32 v213, -v252, v253, v250
	v_fmac_f32_e32 v253, v213, v249
	v_fma_f32 v252, -v252, v253, v250
	v_div_fmas_f32 v252, v252, v249, v253
	v_div_fixup_f32 v253, v252, v251, 1.0
	v_mul_f32_e32 v240, v240, v253
	v_mul_f32_e32 v241, v241, v253
	v_mul_f32_e32 v242, v242, v253
	v_mul_f32_e32 v243, v243, v253
	v_mul_f32_e32 v245, v245, v253
	v_mul_f32_e32 v246, v246, v253
	v_mul_f32_e32 v247, v247, v253
	v_mul_f32_e32 v248, v248, v253
	v_mul_f32_e32 v240, v224, v240
	v_mul_f32_e32 v241, v225, v241
	v_mul_f32_e32 v242, v226, v242
	v_mul_f32_e32 v243, v227, v243
	v_mul_f32_e32 v245, v228, v245
	v_mul_f32_e32 v246, v229, v246
	v_mul_f32_e32 v247, v230, v247
	v_mul_f32_e32 v248, v231, v248
	v_add_u32_e32 v249, 0x1a000, v212
	v_mov_b32_dpp v232, v240 quad_perm:[1,0,3,2] row_mask:0xf bank_mask:0xf bound_ctrl:1
	v_mov_b32_dpp v233, v241 quad_perm:[1,0,3,2] row_mask:0xf bank_mask:0xf bound_ctrl:1
	v_mov_b32_dpp v234, v242 quad_perm:[1,0,3,2] row_mask:0xf bank_mask:0xf bound_ctrl:1
	v_mov_b32_dpp v235, v243 quad_perm:[1,0,3,2] row_mask:0xf bank_mask:0xf bound_ctrl:1
	v_mov_b32_dpp v2, v245 quad_perm:[1,0,3,2] row_mask:0xf bank_mask:0xf bound_ctrl:1
	v_mov_b32_dpp v3, v246 quad_perm:[1,0,3,2] row_mask:0xf bank_mask:0xf bound_ctrl:1
	v_mov_b32_dpp v5, v247 quad_perm:[1,0,3,2] row_mask:0xf bank_mask:0xf bound_ctrl:1
	v_mov_b32_dpp v151, v248 quad_perm:[1,0,3,2] row_mask:0xf bank_mask:0xf bound_ctrl:1
	v_cvt_pk_bf16_f32 v232, v240, v232
	v_cvt_pk_bf16_f32 v233, v233, v241
	v_cndmask_b32_e64 v232, v233, v232, s[60:61]
	global_store_dword v249, v232, s[58:59] offset:0 sc1
	v_cvt_pk_bf16_f32 v234, v242, v234
	v_cvt_pk_bf16_f32 v235, v235, v243
	v_cndmask_b32_e64 v234, v235, v234, s[60:61]
	global_store_dword v249, v234, s[58:59] offset:128 sc1
	v_cvt_pk_bf16_f32 v2, v245, v2
	v_cvt_pk_bf16_f32 v3, v3, v246
	v_cndmask_b32_e64 v2, v3, v2, s[60:61]
	global_store_dword v249, v2, s[58:59] offset:256 sc1
	v_cvt_pk_bf16_f32 v5, v247, v5
	v_cvt_pk_bf16_f32 v151, v151, v248
	v_cndmask_b32_e64 v5, v151, v5, s[60:61]
	global_store_dword v249, v5, s[58:59] offset:384 sc1
	s_waitcnt vmcnt(60)
	v_lshlrev_b32_e32 v250, 16, v220
	v_mul_f32_e32 v249, v145, v6
	v_fma_f32 v240, -v17, v249, v250
	v_and_b32_e32 v250, 0xffff0000, v220
	v_mul_f32_e32 v249, v129, v6
	v_fma_f32 v241, -v17, v249, v250
	v_lshlrev_b32_e32 v250, 16, v221
	v_mul_f32_e32 v249, v113, v6
	v_fma_f32 v242, -v17, v249, v250
	v_and_b32_e32 v250, 0xffff0000, v221
	v_mul_f32_e32 v249, v97, v6
	v_fma_f32 v243, -v17, v249, v250
	v_lshlrev_b32_e32 v250, 16, v222
	v_mul_f32_e32 v249, v81, v6
	v_fma_f32 v245, -v17, v249, v250
	v_and_b32_e32 v250, 0xffff0000, v222
	v_mul_f32_e32 v249, v65, v6
	v_fma_f32 v246, -v17, v249, v250
	v_lshlrev_b32_e32 v250, 16, v223
	v_mul_f32_e32 v249, v49, v6
	v_fma_f32 v247, -v17, v249, v250
	v_and_b32_e32 v250, 0xffff0000, v223
	v_mul_f32_e32 v249, v33, v6
	v_fma_f32 v248, -v17, v249, v250
	v_mul_f32_e32 v251, v241, v241
	v_fmac_f32_e32 v251, v240, v240
	v_fmac_f32_e32 v251, v242, v242
	v_fmac_f32_e32 v251, v243, v243
	v_fmac_f32_e32 v251, v245, v245
	v_fmac_f32_e32 v251, v246, v246
	v_fmac_f32_e32 v251, v247, v247
	v_fmac_f32_e32 v251, v248, v248
	s_nop 1
	v_add_f32_dpp v251, v251, v251 quad_perm:[1,0,3,2] row_mask:0xf bank_mask:0xf bound_ctrl:1
	s_nop 1
	v_add_f32_dpp v251, v251, v251 quad_perm:[2,3,0,1] row_mask:0xf bank_mask:0xf bound_ctrl:1
	s_nop 1
	v_add_f32_dpp v251, v251, v251 row_half_mirror row_mask:0xf bank_mask:0xf bound_ctrl:1
	s_nop 1
	v_add_f32_dpp v251, v251, v251 row_mirror row_mask:0xf bank_mask:0xf bound_ctrl:1
	ds_bpermute_b32 v252, v0, v251
	s_waitcnt lgkmcnt(0)
	v_add_f32_e32 v251, v251, v252
	v_fmamk_f32 v251, v251, 0x3b800000, v238
	v_mul_f32_e32 v252, 0x4f800000, v251
	v_cmp_gt_f32_e32 vcc, s24, v251
	s_nop 1
	v_cndmask_b32_e32 v251, v251, v252, vcc
	v_sqrt_f32_e32 v252, v251
	s_nop 0
	v_add_u32_e32 v249, -1, v252
	v_fma_f32 v250, -v249, v252, v251
	v_cmp_ge_f32_e64 s[6:7], 0, v250
	v_add_u32_e32 v250, 1, v252
	s_nop 0
	v_cndmask_b32_e64 v249, v252, v249, s[6:7]
	v_fma_f32 v252, -v250, v252, v251
	v_cmp_lt_f32_e64 s[6:7], 0, v252
	s_nop 1
	v_cndmask_b32_e64 v252, v249, v250, s[6:7]
	v_mul_f32_e32 v249, 0x37800000, v252
	v_cndmask_b32_e32 v252, v252, v249, vcc
	v_cmp_class_f32_e32 vcc, v251, v239
	s_nop 1
	v_cndmask_b32_e32 v251, v252, v251, vcc
	v_div_scale_f32 v252, s[2:3], v251, v251, 1.0
	v_rcp_f32_e32 v249, v252
	s_nop 0
	v_fma_f32 v250, -v252, v249, 1.0
	v_fmac_f32_e32 v249, v250, v249
	v_div_scale_f32 v250, vcc, 1.0, v251, 1.0
	v_mul_f32_e32 v253, v250, v249
	v_fma_f32 v213, -v252, v253, v250
	v_fmac_f32_e32 v253, v213, v249
	v_fma_f32 v252, -v252, v253, v250
	v_div_fmas_f32 v252, v252, v249, v253
	v_div_fixup_f32 v253, v252, v251, 1.0
	v_mul_f32_e32 v240, v240, v253
	v_mul_f32_e32 v241, v241, v253
	v_mul_f32_e32 v242, v242, v253
	v_mul_f32_e32 v243, v243, v253
	v_mul_f32_e32 v245, v245, v253
	v_mul_f32_e32 v246, v246, v253
	v_mul_f32_e32 v247, v247, v253
	v_mul_f32_e32 v248, v248, v253
	v_mul_f32_e32 v240, v224, v240
	v_mul_f32_e32 v241, v225, v241
	v_mul_f32_e32 v242, v226, v242
	v_mul_f32_e32 v243, v227, v243
	v_mul_f32_e32 v245, v228, v245
	v_mul_f32_e32 v246, v229, v246
	v_mul_f32_e32 v247, v230, v247
	v_mul_f32_e32 v248, v231, v248
	v_add_u32_e32 v249, 0x1b000, v212
	v_mov_b32_dpp v232, v240 quad_perm:[1,0,3,2] row_mask:0xf bank_mask:0xf bound_ctrl:1
	v_mov_b32_dpp v233, v241 quad_perm:[1,0,3,2] row_mask:0xf bank_mask:0xf bound_ctrl:1
	v_mov_b32_dpp v234, v242 quad_perm:[1,0,3,2] row_mask:0xf bank_mask:0xf bound_ctrl:1
	v_mov_b32_dpp v235, v243 quad_perm:[1,0,3,2] row_mask:0xf bank_mask:0xf bound_ctrl:1
	v_mov_b32_dpp v2, v245 quad_perm:[1,0,3,2] row_mask:0xf bank_mask:0xf bound_ctrl:1
	v_mov_b32_dpp v3, v246 quad_perm:[1,0,3,2] row_mask:0xf bank_mask:0xf bound_ctrl:1
	v_mov_b32_dpp v5, v247 quad_perm:[1,0,3,2] row_mask:0xf bank_mask:0xf bound_ctrl:1
	v_mov_b32_dpp v151, v248 quad_perm:[1,0,3,2] row_mask:0xf bank_mask:0xf bound_ctrl:1
	v_cvt_pk_bf16_f32 v232, v240, v232
	v_cvt_pk_bf16_f32 v233, v233, v241
	v_cndmask_b32_e64 v232, v233, v232, s[60:61]
	global_store_dword v249, v232, s[58:59] offset:0 sc1
	v_cvt_pk_bf16_f32 v234, v242, v234
	v_cvt_pk_bf16_f32 v235, v235, v243
	v_cndmask_b32_e64 v234, v235, v234, s[60:61]
	global_store_dword v249, v234, s[58:59] offset:128 sc1
	v_cvt_pk_bf16_f32 v2, v245, v2
	v_cvt_pk_bf16_f32 v3, v3, v246
	v_cndmask_b32_e64 v2, v3, v2, s[60:61]
	global_store_dword v249, v2, s[58:59] offset:256 sc1
	v_cvt_pk_bf16_f32 v5, v247, v5
	v_cvt_pk_bf16_f32 v151, v151, v248
	v_cndmask_b32_e64 v5, v151, v5, s[60:61]
	global_store_dword v249, v5, s[58:59] offset:384 sc1
	s_branch .Lep_done

.LBB0_1045:
	s_or_b64 exec, exec, s[4:5]
	v_mov_b32_e32 v17, v221
	v_mov_b32_e32 v98, v220
	v_lshl_add_u32 v17, v17, 2, s21
	ds_read2_b32 v[96:97], v17 offset1:1
	ds_read2_b32 v[30:31], v17 offset0:2 offset1:3
	ds_read2_b32 v[28:29], v17 offset0:8 offset1:9
	ds_read2_b32 v[26:27], v17 offset0:10 offset1:11
	ds_read2_b32 v[24:25], v17 offset0:16 offset1:17
	ds_read2_b32 v[22:23], v17 offset0:18 offset1:19
	ds_read2_b32 v[20:21], v17 offset0:24 offset1:25
	ds_read2_b32 v[18:19], v17 offset0:26 offset1:27
	s_mov_b32 s21, s80
	s_mul_hi_i32 s5, s21, s2
	s_mul_i32 s4, s21, s2
	s_lshl_b64 s[4:5], s[4:5], 1
	s_add_u32 s4, s50, s4
	s_addc_u32 s5, s51, s5
	s_lshl_b32 s22, s21, 1
	v_and_b32_e32 v99, 1, v219
	v_cmp_eq_u32_e64 s[68:69], 0, v99
	v_mul_lo_u32 v98, v220, s21
	v_lshlrev_b32_e32 v98, 3, v98
	v_lshl_add_u32 v98, v219, 1, v98
	v_mul_u32_u24_e32 v17, 62, v99
	v_add_u32_e32 v98, v98, v17
	s_waitcnt lgkmcnt(0)
	v_rcp_f32_e32 v96, v96
	v_rcp_f32_e32 v97, v97
	v_rcp_f32_e32 v30, v30
	v_rcp_f32_e32 v31, v31
	v_rcp_f32_e32 v28, v28
	v_rcp_f32_e32 v29, v29
	v_rcp_f32_e32 v26, v26
	v_rcp_f32_e32 v27, v27
	v_rcp_f32_e32 v24, v24
	v_rcp_f32_e32 v25, v25
	v_rcp_f32_e32 v22, v22
	v_rcp_f32_e32 v23, v23
	v_rcp_f32_e32 v20, v20
	v_rcp_f32_e32 v21, v21
	v_rcp_f32_e32 v18, v18
	v_rcp_f32_e32 v19, v19
	v_mov_b32_e32 v99, v98
	v_mul_f32_e32 v64, v64, v96
	v_mul_f32_e32 v80, v80, v96
	v_mul_f32_e32 v48, v48, v96
	v_mul_f32_e32 v32, v32, v96
	v_mov_b32_dpp v100, v64 quad_perm:[1,0,3,2] row_mask:0xf bank_mask:0xf bound_ctrl:1
	v_mov_b32_dpp v101, v80 quad_perm:[1,0,3,2] row_mask:0xf bank_mask:0xf bound_ctrl:1
	v_mov_b32_dpp v102, v48 quad_perm:[1,0,3,2] row_mask:0xf bank_mask:0xf bound_ctrl:1
	v_mov_b32_dpp v103, v32 quad_perm:[1,0,3,2] row_mask:0xf bank_mask:0xf bound_ctrl:1
	v_cvt_pk_bf16_f32 v100, v64, v100
	v_cvt_pk_bf16_f32 v101, v101, v80
	v_cndmask_b32_e64 v100, v101, v100, s[68:69]
	global_store_dword v99, v100, s[4:5] offset:0 sc1
	v_cvt_pk_bf16_f32 v102, v48, v102
	v_cvt_pk_bf16_f32 v103, v103, v32
	v_cndmask_b32_e64 v102, v103, v102, s[68:69]
	global_store_dword v99, v102, s[4:5] offset:128 sc1
	s_mul_i32 s23, s22, 1
	v_add_u32_e32 v99, s23, v98
	v_mul_f32_e32 v65, v65, v97
	v_mul_f32_e32 v81, v81, v97
	v_mul_f32_e32 v49, v49, v97
	v_mul_f32_e32 v33, v33, v97
	v_mov_b32_dpp v100, v65 quad_perm:[1,0,3,2] row_mask:0xf bank_mask:0xf bound_ctrl:1
	v_mov_b32_dpp v101, v81 quad_perm:[1,0,3,2] row_mask:0xf bank_mask:0xf bound_ctrl:1
	v_mov_b32_dpp v102, v49 quad_perm:[1,0,3,2] row_mask:0xf bank_mask:0xf bound_ctrl:1
	v_mov_b32_dpp v103, v33 quad_perm:[1,0,3,2] row_mask:0xf bank_mask:0xf bound_ctrl:1
	v_cvt_pk_bf16_f32 v100, v65, v100
	v_cvt_pk_bf16_f32 v101, v101, v81
	v_cndmask_b32_e64 v100, v101, v100, s[68:69]
	global_store_dword v99, v100, s[4:5] offset:0 sc1
	v_cvt_pk_bf16_f32 v102, v49, v102
	v_cvt_pk_bf16_f32 v103, v103, v33
	v_cndmask_b32_e64 v102, v103, v102, s[68:69]
	global_store_dword v99, v102, s[4:5] offset:128 sc1
	s_mul_i32 s23, s22, 2
	v_add_u32_e32 v99, s23, v98
	v_mul_f32_e32 v66, v66, v30
	v_mul_f32_e32 v82, v82, v30
	v_mul_f32_e32 v50, v50, v30
	v_mul_f32_e32 v34, v34, v30
	v_mov_b32_dpp v100, v66 quad_perm:[1,0,3,2] row_mask:0xf bank_mask:0xf bound_ctrl:1
	v_mov_b32_dpp v101, v82 quad_perm:[1,0,3,2] row_mask:0xf bank_mask:0xf bound_ctrl:1
	v_mov_b32_dpp v102, v50 quad_perm:[1,0,3,2] row_mask:0xf bank_mask:0xf bound_ctrl:1
	v_mov_b32_dpp v103, v34 quad_perm:[1,0,3,2] row_mask:0xf bank_mask:0xf bound_ctrl:1
	v_cvt_pk_bf16_f32 v100, v66, v100
	v_cvt_pk_bf16_f32 v101, v101, v82
	v_cndmask_b32_e64 v100, v101, v100, s[68:69]
	global_store_dword v99, v100, s[4:5] offset:0 sc1
	v_cvt_pk_bf16_f32 v102, v50, v102
	v_cvt_pk_bf16_f32 v103, v103, v34
	v_cndmask_b32_e64 v102, v103, v102, s[68:69]
	global_store_dword v99, v102, s[4:5] offset:128 sc1
	s_mul_i32 s23, s22, 3
	v_add_u32_e32 v99, s23, v98
	v_mul_f32_e32 v67, v67, v31
	v_mul_f32_e32 v83, v83, v31
	v_mul_f32_e32 v51, v51, v31
	v_mul_f32_e32 v35, v35, v31
	v_mov_b32_dpp v100, v67 quad_perm:[1,0,3,2] row_mask:0xf bank_mask:0xf bound_ctrl:1
	v_mov_b32_dpp v101, v83 quad_perm:[1,0,3,2] row_mask:0xf bank_mask:0xf bound_ctrl:1
	v_mov_b32_dpp v102, v51 quad_perm:[1,0,3,2] row_mask:0xf bank_mask:0xf bound_ctrl:1
	v_mov_b32_dpp v103, v35 quad_perm:[1,0,3,2] row_mask:0xf bank_mask:0xf bound_ctrl:1
	v_cvt_pk_bf16_f32 v100, v67, v100
	v_cvt_pk_bf16_f32 v101, v101, v83
	v_cndmask_b32_e64 v100, v101, v100, s[68:69]
	global_store_dword v99, v100, s[4:5] offset:0 sc1
	v_cvt_pk_bf16_f32 v102, v51, v102
	v_cvt_pk_bf16_f32 v103, v103, v35
	v_cndmask_b32_e64 v102, v103, v102, s[68:69]
	global_store_dword v99, v102, s[4:5] offset:128 sc1
	s_mul_i32 s23, s22, 8
	v_add_u32_e32 v99, s23, v98
	v_mul_f32_e32 v68, v68, v28
	v_mul_f32_e32 v84, v84, v28
	v_mul_f32_e32 v52, v52, v28
	v_mul_f32_e32 v36, v36, v28
	v_mov_b32_dpp v100, v68 quad_perm:[1,0,3,2] row_mask:0xf bank_mask:0xf bound_ctrl:1
	v_mov_b32_dpp v101, v84 quad_perm:[1,0,3,2] row_mask:0xf bank_mask:0xf bound_ctrl:1
	v_mov_b32_dpp v102, v52 quad_perm:[1,0,3,2] row_mask:0xf bank_mask:0xf bound_ctrl:1
	v_mov_b32_dpp v103, v36 quad_perm:[1,0,3,2] row_mask:0xf bank_mask:0xf bound_ctrl:1
	v_cvt_pk_bf16_f32 v100, v68, v100
	v_cvt_pk_bf16_f32 v101, v101, v84
	v_cndmask_b32_e64 v100, v101, v100, s[68:69]
	global_store_dword v99, v100, s[4:5] offset:0 sc1
	v_cvt_pk_bf16_f32 v102, v52, v102
	v_cvt_pk_bf16_f32 v103, v103, v36
	v_cndmask_b32_e64 v102, v103, v102, s[68:69]
	global_store_dword v99, v102, s[4:5] offset:128 sc1
	s_mul_i32 s23, s22, 9
	v_add_u32_e32 v99, s23, v98
	v_mul_f32_e32 v69, v69, v29
	v_mul_f32_e32 v85, v85, v29
	v_mul_f32_e32 v53, v53, v29
	v_mul_f32_e32 v37, v37, v29
	v_mov_b32_dpp v100, v69 quad_perm:[1,0,3,2] row_mask:0xf bank_mask:0xf bound_ctrl:1
	v_mov_b32_dpp v101, v85 quad_perm:[1,0,3,2] row_mask:0xf bank_mask:0xf bound_ctrl:1
	v_mov_b32_dpp v102, v53 quad_perm:[1,0,3,2] row_mask:0xf bank_mask:0xf bound_ctrl:1
	v_mov_b32_dpp v103, v37 quad_perm:[1,0,3,2] row_mask:0xf bank_mask:0xf bound_ctrl:1
	v_cvt_pk_bf16_f32 v100, v69, v100
	v_cvt_pk_bf16_f32 v101, v101, v85
	v_cndmask_b32_e64 v100, v101, v100, s[68:69]
	global_store_dword v99, v100, s[4:5] offset:0 sc1
	v_cvt_pk_bf16_f32 v102, v53, v102
	v_cvt_pk_bf16_f32 v103, v103, v37
	v_cndmask_b32_e64 v102, v103, v102, s[68:69]
	global_store_dword v99, v102, s[4:5] offset:128 sc1
	s_mul_i32 s23, s22, 10
	v_add_u32_e32 v99, s23, v98
	v_mul_f32_e32 v70, v70, v26
	v_mul_f32_e32 v86, v86, v26
	v_mul_f32_e32 v54, v54, v26
	v_mul_f32_e32 v38, v38, v26
	v_mov_b32_dpp v100, v70 quad_perm:[1,0,3,2] row_mask:0xf bank_mask:0xf bound_ctrl:1
	v_mov_b32_dpp v101, v86 quad_perm:[1,0,3,2] row_mask:0xf bank_mask:0xf bound_ctrl:1
	v_mov_b32_dpp v102, v54 quad_perm:[1,0,3,2] row_mask:0xf bank_mask:0xf bound_ctrl:1
	v_mov_b32_dpp v103, v38 quad_perm:[1,0,3,2] row_mask:0xf bank_mask:0xf bound_ctrl:1
	v_cvt_pk_bf16_f32 v100, v70, v100
	v_cvt_pk_bf16_f32 v101, v101, v86
	v_cndmask_b32_e64 v100, v101, v100, s[68:69]
	global_store_dword v99, v100, s[4:5] offset:0 sc1
	v_cvt_pk_bf16_f32 v102, v54, v102
	v_cvt_pk_bf16_f32 v103, v103, v38
	v_cndmask_b32_e64 v102, v103, v102, s[68:69]
	global_store_dword v99, v102, s[4:5] offset:128 sc1
	s_mul_i32 s23, s22, 11
	v_add_u32_e32 v99, s23, v98
	v_mul_f32_e32 v71, v71, v27
	v_mul_f32_e32 v87, v87, v27
	v_mul_f32_e32 v55, v55, v27
	v_mul_f32_e32 v39, v39, v27
	v_mov_b32_dpp v100, v71 quad_perm:[1,0,3,2] row_mask:0xf bank_mask:0xf bound_ctrl:1
	v_mov_b32_dpp v101, v87 quad_perm:[1,0,3,2] row_mask:0xf bank_mask:0xf bound_ctrl:1
	v_mov_b32_dpp v102, v55 quad_perm:[1,0,3,2] row_mask:0xf bank_mask:0xf bound_ctrl:1
	v_mov_b32_dpp v103, v39 quad_perm:[1,0,3,2] row_mask:0xf bank_mask:0xf bound_ctrl:1
	v_cvt_pk_bf16_f32 v100, v71, v100
	v_cvt_pk_bf16_f32 v101, v101, v87
	v_cndmask_b32_e64 v100, v101, v100, s[68:69]
	global_store_dword v99, v100, s[4:5] offset:0 sc1
	v_cvt_pk_bf16_f32 v102, v55, v102
	v_cvt_pk_bf16_f32 v103, v103, v39
	v_cndmask_b32_e64 v102, v103, v102, s[68:69]
	global_store_dword v99, v102, s[4:5] offset:128 sc1
	s_mul_i32 s23, s22, 16
	v_add_u32_e32 v99, s23, v98
	v_mul_f32_e32 v72, v72, v24
	v_mul_f32_e32 v88, v88, v24
	v_mul_f32_e32 v56, v56, v24
	v_mul_f32_e32 v40, v40, v24
	v_mov_b32_dpp v100, v72 quad_perm:[1,0,3,2] row_mask:0xf bank_mask:0xf bound_ctrl:1
	v_mov_b32_dpp v101, v88 quad_perm:[1,0,3,2] row_mask:0xf bank_mask:0xf bound_ctrl:1
	v_mov_b32_dpp v102, v56 quad_perm:[1,0,3,2] row_mask:0xf bank_mask:0xf bound_ctrl:1
	v_mov_b32_dpp v103, v40 quad_perm:[1,0,3,2] row_mask:0xf bank_mask:0xf bound_ctrl:1
	v_cvt_pk_bf16_f32 v100, v72, v100
	v_cvt_pk_bf16_f32 v101, v101, v88
	v_cndmask_b32_e64 v100, v101, v100, s[68:69]
	global_store_dword v99, v100, s[4:5] offset:0 sc1
	v_cvt_pk_bf16_f32 v102, v56, v102
	v_cvt_pk_bf16_f32 v103, v103, v40
	v_cndmask_b32_e64 v102, v103, v102, s[68:69]
	global_store_dword v99, v102, s[4:5] offset:128 sc1
	s_mul_i32 s23, s22, 17
	v_add_u32_e32 v99, s23, v98
	v_mul_f32_e32 v73, v73, v25
	v_mul_f32_e32 v89, v89, v25
	v_mul_f32_e32 v57, v57, v25
	v_mul_f32_e32 v41, v41, v25
	v_mov_b32_dpp v100, v73 quad_perm:[1,0,3,2] row_mask:0xf bank_mask:0xf bound_ctrl:1
	v_mov_b32_dpp v101, v89 quad_perm:[1,0,3,2] row_mask:0xf bank_mask:0xf bound_ctrl:1
	v_mov_b32_dpp v102, v57 quad_perm:[1,0,3,2] row_mask:0xf bank_mask:0xf bound_ctrl:1
	v_mov_b32_dpp v103, v41 quad_perm:[1,0,3,2] row_mask:0xf bank_mask:0xf bound_ctrl:1
	v_cvt_pk_bf16_f32 v100, v73, v100
	v_cvt_pk_bf16_f32 v101, v101, v89
	v_cndmask_b32_e64 v100, v101, v100, s[68:69]
	global_store_dword v99, v100, s[4:5] offset:0 sc1
	v_cvt_pk_bf16_f32 v102, v57, v102
	v_cvt_pk_bf16_f32 v103, v103, v41
	v_cndmask_b32_e64 v102, v103, v102, s[68:69]
	global_store_dword v99, v102, s[4:5] offset:128 sc1
	s_mul_i32 s23, s22, 18
	v_add_u32_e32 v99, s23, v98
	v_mul_f32_e32 v74, v74, v22
	v_mul_f32_e32 v90, v90, v22
	v_mul_f32_e32 v58, v58, v22
	v_mul_f32_e32 v42, v42, v22
	v_mov_b32_dpp v100, v74 quad_perm:[1,0,3,2] row_mask:0xf bank_mask:0xf bound_ctrl:1
	v_mov_b32_dpp v101, v90 quad_perm:[1,0,3,2] row_mask:0xf bank_mask:0xf bound_ctrl:1
	v_mov_b32_dpp v102, v58 quad_perm:[1,0,3,2] row_mask:0xf bank_mask:0xf bound_ctrl:1
	v_mov_b32_dpp v103, v42 quad_perm:[1,0,3,2] row_mask:0xf bank_mask:0xf bound_ctrl:1
	v_cvt_pk_bf16_f32 v100, v74, v100
	v_cvt_pk_bf16_f32 v101, v101, v90
	v_cndmask_b32_e64 v100, v101, v100, s[68:69]
	global_store_dword v99, v100, s[4:5] offset:0 sc1
	v_cvt_pk_bf16_f32 v102, v58, v102
	v_cvt_pk_bf16_f32 v103, v103, v42
	v_cndmask_b32_e64 v102, v103, v102, s[68:69]
	global_store_dword v99, v102, s[4:5] offset:128 sc1
	s_mul_i32 s23, s22, 19
	v_add_u32_e32 v99, s23, v98
	v_mul_f32_e32 v75, v75, v23
	v_mul_f32_e32 v91, v91, v23
	v_mul_f32_e32 v59, v59, v23
	v_mul_f32_e32 v43, v43, v23
	v_mov_b32_dpp v100, v75 quad_perm:[1,0,3,2] row_mask:0xf bank_mask:0xf bound_ctrl:1
	v_mov_b32_dpp v101, v91 quad_perm:[1,0,3,2] row_mask:0xf bank_mask:0xf bound_ctrl:1
	v_mov_b32_dpp v102, v59 quad_perm:[1,0,3,2] row_mask:0xf bank_mask:0xf bound_ctrl:1
	v_mov_b32_dpp v103, v43 quad_perm:[1,0,3,2] row_mask:0xf bank_mask:0xf bound_ctrl:1
	v_cvt_pk_bf16_f32 v100, v75, v100
	v_cvt_pk_bf16_f32 v101, v101, v91
	v_cndmask_b32_e64 v100, v101, v100, s[68:69]
	global_store_dword v99, v100, s[4:5] offset:0 sc1
	v_cvt_pk_bf16_f32 v102, v59, v102
	v_cvt_pk_bf16_f32 v103, v103, v43
	v_cndmask_b32_e64 v102, v103, v102, s[68:69]
	global_store_dword v99, v102, s[4:5] offset:128 sc1
	s_mul_i32 s23, s22, 24
	v_add_u32_e32 v99, s23, v98
	v_mul_f32_e32 v76, v76, v20
	v_mul_f32_e32 v92, v92, v20
	v_mul_f32_e32 v60, v60, v20
	v_mul_f32_e32 v44, v44, v20
	v_mov_b32_dpp v100, v76 quad_perm:[1,0,3,2] row_mask:0xf bank_mask:0xf bound_ctrl:1
	v_mov_b32_dpp v101, v92 quad_perm:[1,0,3,2] row_mask:0xf bank_mask:0xf bound_ctrl:1
	v_mov_b32_dpp v102, v60 quad_perm:[1,0,3,2] row_mask:0xf bank_mask:0xf bound_ctrl:1
	v_mov_b32_dpp v103, v44 quad_perm:[1,0,3,2] row_mask:0xf bank_mask:0xf bound_ctrl:1
	v_cvt_pk_bf16_f32 v100, v76, v100
	v_cvt_pk_bf16_f32 v101, v101, v92
	v_cndmask_b32_e64 v100, v101, v100, s[68:69]
	global_store_dword v99, v100, s[4:5] offset:0 sc1
	v_cvt_pk_bf16_f32 v102, v60, v102
	v_cvt_pk_bf16_f32 v103, v103, v44
	v_cndmask_b32_e64 v102, v103, v102, s[68:69]
	global_store_dword v99, v102, s[4:5] offset:128 sc1
	s_mul_i32 s23, s22, 25
	v_add_u32_e32 v99, s23, v98
	v_mul_f32_e32 v77, v77, v21
	v_mul_f32_e32 v93, v93, v21
	v_mul_f32_e32 v61, v61, v21
	v_mul_f32_e32 v45, v45, v21
	v_mov_b32_dpp v100, v77 quad_perm:[1,0,3,2] row_mask:0xf bank_mask:0xf bound_ctrl:1
	v_mov_b32_dpp v101, v93 quad_perm:[1,0,3,2] row_mask:0xf bank_mask:0xf bound_ctrl:1
	v_mov_b32_dpp v102, v61 quad_perm:[1,0,3,2] row_mask:0xf bank_mask:0xf bound_ctrl:1
	v_mov_b32_dpp v103, v45 quad_perm:[1,0,3,2] row_mask:0xf bank_mask:0xf bound_ctrl:1
	v_cvt_pk_bf16_f32 v100, v77, v100
	v_cvt_pk_bf16_f32 v101, v101, v93
	v_cndmask_b32_e64 v100, v101, v100, s[68:69]
	global_store_dword v99, v100, s[4:5] offset:0 sc1
	v_cvt_pk_bf16_f32 v102, v61, v102
	v_cvt_pk_bf16_f32 v103, v103, v45
	v_cndmask_b32_e64 v102, v103, v102, s[68:69]
	global_store_dword v99, v102, s[4:5] offset:128 sc1
	s_mul_i32 s23, s22, 26
	v_add_u32_e32 v99, s23, v98
	v_mul_f32_e32 v78, v78, v18
	v_mul_f32_e32 v94, v94, v18
	v_mul_f32_e32 v62, v62, v18
	v_mul_f32_e32 v46, v46, v18
	v_mov_b32_dpp v100, v78 quad_perm:[1,0,3,2] row_mask:0xf bank_mask:0xf bound_ctrl:1
	v_mov_b32_dpp v101, v94 quad_perm:[1,0,3,2] row_mask:0xf bank_mask:0xf bound_ctrl:1
	v_mov_b32_dpp v102, v62 quad_perm:[1,0,3,2] row_mask:0xf bank_mask:0xf bound_ctrl:1
	v_mov_b32_dpp v103, v46 quad_perm:[1,0,3,2] row_mask:0xf bank_mask:0xf bound_ctrl:1
	v_cvt_pk_bf16_f32 v100, v78, v100
	v_cvt_pk_bf16_f32 v101, v101, v94
	v_cndmask_b32_e64 v100, v101, v100, s[68:69]
	global_store_dword v99, v100, s[4:5] offset:0 sc1
	v_cvt_pk_bf16_f32 v102, v62, v102
	v_cvt_pk_bf16_f32 v103, v103, v46
	v_cndmask_b32_e64 v102, v103, v102, s[68:69]
	global_store_dword v99, v102, s[4:5] offset:128 sc1
	s_mul_i32 s23, s22, 27
	v_add_u32_e32 v99, s23, v98
	v_mul_f32_e32 v79, v79, v19
	v_mul_f32_e32 v95, v95, v19
	v_mul_f32_e32 v63, v63, v19
	v_mul_f32_e32 v47, v47, v19
	v_mov_b32_dpp v100, v79 quad_perm:[1,0,3,2] row_mask:0xf bank_mask:0xf bound_ctrl:1
	v_mov_b32_dpp v101, v95 quad_perm:[1,0,3,2] row_mask:0xf bank_mask:0xf bound_ctrl:1
	v_mov_b32_dpp v102, v63 quad_perm:[1,0,3,2] row_mask:0xf bank_mask:0xf bound_ctrl:1
	v_mov_b32_dpp v103, v47 quad_perm:[1,0,3,2] row_mask:0xf bank_mask:0xf bound_ctrl:1
	v_cvt_pk_bf16_f32 v100, v79, v100
	v_cvt_pk_bf16_f32 v101, v101, v95
	v_cndmask_b32_e64 v100, v101, v100, s[68:69]
	global_store_dword v99, v100, s[4:5] offset:0 sc1
	v_cvt_pk_bf16_f32 v102, v63, v102
	v_cvt_pk_bf16_f32 v103, v103, v47
	v_cndmask_b32_e64 v102, v103, v102, s[68:69]
	global_store_dword v99, v102, s[4:5] offset:128 sc1
